# MLA lazy rescale: on a rescale the row reference is set 1.0 (log2) above the tile row max, so fewer rescale events; same fp8 P / f32 softmax math
# speedup vs baseline: 1.0082x; 1.0015x over previous
; __device__ __forceinline__ void finishSM9(f32x16& p0, f32x16& p1, float alpha, float& l_reg, v8i32& p8) {
; #pragma unroll
;   for (int r = 0; r < 16; ++r) { p0[r] = __builtin_amdgcn_exp2f(p0[r]); p1[r] = __builtin_amdgcn_exp2f(p1[r]); }
;   float ps = 0;
; #pragma unroll
;   for (int r = 0; r < 16; ++r) ps += p0[r];
; #pragma unroll
;   for (int r = 0; r < 16; ++r) ps += p1[r];
;   { auto rr = __builtin_amdgcn_permlane32_swap(__float_as_uint(ps), __float_as_uint(ps), false, false);
;     ps = __uint_as_float(rr[0]) + __uint_as_float(rr[1]); }
;   l_reg = l_reg * alpha + ps;
; #pragma unroll
;   for (int g = 0; g < 4; ++g) {
;     int w = __builtin_amdgcn_cvt_pk_fp8_f32(p0[4 * g], p0[4 * g + 1], 0, false); p8[g] = __builtin_amdgcn_cvt_pk_fp8_f32(p0[4 * g + 2], p0[4 * g + 3], w, true);
;     int u = __builtin_amdgcn_cvt_pk_fp8_f32(p1[4 * g], p1[4 * g + 1], 0, false); p8[4 + g] = __builtin_amdgcn_cvt_pk_fp8_f32(p1[4 * g + 2], p1[4 * g + 3], u, true); }
; }
; __device__ __forceinline__ void pv8(f32x16* o, const char* Vt, const v8i32 p8, int r32, int hi) {
;   const int sw = (r32 >> 2) & 3, a0 = r32 * 64 + (((hi * 2) ^ sw) << 4), a1 = r32 * 64 + (((hi * 2 + 1) ^ sw) << 4);
; #pragma unroll
;   for (int d0 = 0; d0 < 4; ++d0) {
;     const v8i32 vf = cat8(*reinterpret_cast<const v4i32*>(Vt + d0 * 2048 + a0), *reinterpret_cast<const v4i32*>(Vt + d0 * 2048 + a1));
;     o[d0] = __builtin_amdgcn_mfma_scale_f32_32x32x64_f8f6f4(p8, vf, o[d0], 0, 0, 0, 127, 0, 127); }
; }
; __device__ __forceinline__ void qkt9(f32x16& p0, f32x16& p1, const char* Kn, const char* Kr, const v8i32* qf, const float init, int r32, int hi) {
; #pragma unroll
;   for (int r = 0; r < 16; ++r) { p0[r] = init; p1[r] = init; }
; #pragma unroll
;   for (int s = 0; s < 2; ++s) { const int c0 = s * 4 + hi * 2;
;     const v8i32 a0 = cat8(*reinterpret_cast<const v4i32*>(Kn + KN8SW(r32, c0)), *reinterpret_cast<const v4i32*>(Kn + KN8SW(r32, c0 + 1)));
;     const v8i32 a1 = cat8(*reinterpret_cast<const v4i32*>(Kn + 4096 + KN8SW(r32, c0)), *reinterpret_cast<const v4i32*>(Kn + 4096 + KN8SW(r32, c0 + 1)));
;     p0 = __builtin_amdgcn_mfma_scale_f32_32x32x64_f8f6f4(a0, qf[s], p0, 0, 0, 0, 127, 0, 124);
;     p1 = __builtin_amdgcn_mfma_scale_f32_32x32x64_f8f6f4(a1, qf[s], p1, 0, 0, 0, 127, 0, 124); }
;   { const int c0 = hi * 2;
.Lmla_stag_loop:
	ds_read_b128 v[114:117], v215 offset:24576
	ds_read_b128 v[118:121], v216 offset:24576
	ds_read_b128 v[222:225], v215 offset:28672
	ds_read_b128 v[226:229], v216 offset:28672
	v_exp_f32_e32 v0, v82
	v_exp_f32_e32 v177, v83
	v_exp_f32_e32 v179, v84
	v_exp_f32_e32 v254, v85
	v_add_f32_e32 v219, v0, v177
	v_cvt_pk_fp8_f32 v246, v0, v177
	v_add_f32_e32 v219, v179, v219
	v_add_f32_e32 v219, v254, v219
	v_cvt_pk_fp8_f32 v246, v179, v254 op_sel:[0,0,1]
	s_waitcnt lgkmcnt(2)
	v_mfma_scale_f32_32x32x64_f8f6f4 v[114:129], v[114:121], v[146:153], v[230:245], v194, v193 op_sel_hi:[0,0,0]
	v_exp_f32_e32 v0, v86
	v_exp_f32_e32 v177, v87
	v_exp_f32_e32 v179, v88
	v_exp_f32_e32 v254, v89
	v_add_f32_e32 v219, v0, v219
	v_add_f32_e32 v219, v177, v219
	v_cvt_pk_fp8_f32 v247, v0, v177
	v_add_f32_e32 v219, v179, v219
	v_add_f32_e32 v219, v254, v219
	v_cvt_pk_fp8_f32 v247, v179, v254 op_sel:[0,0,1]
	ds_read_b128 v[82:85], v213 offset:24576
	ds_read_b128 v[86:89], v214 offset:24576
	s_waitcnt lgkmcnt(2)
	v_mfma_scale_f32_32x32x64_f8f6f4 v[98:113], v[222:229], v[146:153], v[230:245], v194, v193 op_sel_hi:[0,0,0]
	ds_read_b128 v[222:225], v213 offset:28672
	ds_read_b128 v[226:229], v214 offset:28672
	v_exp_f32_e32 v0, v90
	v_exp_f32_e32 v177, v91
	v_exp_f32_e32 v179, v92
	v_exp_f32_e32 v254, v93
	v_add_f32_e32 v219, v0, v219
	v_add_f32_e32 v219, v177, v219
	v_cvt_pk_fp8_f32 v248, v0, v177
	v_add_f32_e32 v219, v179, v219
	v_add_f32_e32 v219, v254, v219
	v_cvt_pk_fp8_f32 v248, v179, v254 op_sel:[0,0,1]
	v_exp_f32_e32 v0, v94
	v_exp_f32_e32 v177, v95
	v_exp_f32_e32 v179, v96
	v_exp_f32_e32 v254, v97
	v_add_f32_e32 v219, v0, v219
	v_add_f32_e32 v219, v177, v219
	v_cvt_pk_fp8_f32 v249, v0, v177
	v_add_f32_e32 v219, v179, v219
	v_add_f32_e32 v219, v254, v219
	v_cvt_pk_fp8_f32 v249, v179, v254 op_sel:[0,0,1]
	ds_read_b128 v[90:93], v185 offset:36864
	ds_read_b128 v[94:97], v186 offset:36864
	s_waitcnt lgkmcnt(4)
	v_mfma_scale_f32_32x32x64_f8f6f4 v[114:129], v[82:89], v[138:145], v[114:129], v194, v193 op_sel_hi:[0,0,0]
	v_exp_f32_e32 v0, v66
	v_exp_f32_e32 v177, v67
	v_exp_f32_e32 v179, v68
	v_exp_f32_e32 v254, v69
	v_add_f32_e32 v219, v0, v219
	v_add_f32_e32 v219, v177, v219
	v_cvt_pk_fp8_f32 v250, v0, v177
	v_add_f32_e32 v219, v179, v219
	v_add_f32_e32 v219, v254, v219
	v_cvt_pk_fp8_f32 v250, v179, v254 op_sel:[0,0,1]
	s_waitcnt lgkmcnt(2)
	v_mfma_scale_f32_32x32x64_f8f6f4 v[98:113], v[222:229], v[138:145], v[98:113], v194, v193 op_sel_hi:[0,0,0]
	ds_read_b128 v[222:225], v185 offset:38912
	ds_read_b128 v[226:229], v186 offset:38912
	v_exp_f32_e32 v0, v70
	v_exp_f32_e32 v177, v71
	v_exp_f32_e32 v179, v72
	v_exp_f32_e32 v254, v73
	v_add_f32_e32 v219, v0, v219
	v_add_f32_e32 v219, v177, v219
	v_cvt_pk_fp8_f32 v251, v0, v177
	v_add_f32_e32 v219, v179, v219
	v_add_f32_e32 v219, v254, v219
	v_cvt_pk_fp8_f32 v251, v179, v254 op_sel:[0,0,1]
	v_exp_f32_e32 v0, v74
	v_exp_f32_e32 v177, v75
	v_exp_f32_e32 v179, v76
	v_exp_f32_e32 v254, v77
	v_add_f32_e32 v219, v0, v219
	v_add_f32_e32 v219, v177, v219
	v_cvt_pk_fp8_f32 v252, v0, v177
	v_add_f32_e32 v219, v179, v219
	v_add_f32_e32 v219, v254, v219
	v_cvt_pk_fp8_f32 v252, v179, v254 op_sel:[0,0,1]
	s_waitcnt lgkmcnt(2)
	v_mfma_scale_f32_32x32x64_f8f6f4 v[114:129], v[90:97], v[130:137], v[114:129], v194, v193 op_sel_hi:[0,0,0]
	v_exp_f32_e32 v0, v78
	v_exp_f32_e32 v177, v79
	v_exp_f32_e32 v179, v80
	v_exp_f32_e32 v254, v81
	v_add_f32_e32 v219, v0, v219
	v_add_f32_e32 v219, v177, v219
	v_cvt_pk_fp8_f32 v253, v0, v177
	v_add_f32_e32 v219, v179, v219
	v_add_f32_e32 v219, v254, v219
	v_cvt_pk_fp8_f32 v253, v179, v254 op_sel:[0,0,1]
	ds_read_b128 v[90:93], v185 offset:0
	ds_read_b128 v[94:97], v186 offset:0
	ds_read_b128 v[82:85], v185 offset:2048
	ds_read_b128 v[86:89], v186 offset:2048
	ds_read_b128 v[74:77], v185 offset:4096
	ds_read_b128 v[78:81], v186 offset:4096
	ds_read_b128 v[66:69], v185 offset:6144
	ds_read_b128 v[70:73], v186 offset:6144
	s_waitcnt lgkmcnt(8)
	v_mfma_scale_f32_32x32x64_f8f6f4 v[98:113], v[222:229], v[130:137], v[98:113], v194, v193 op_sel_hi:[0,0,0]
	v_mov_b32_e32 v0, v219
	s_nop 1
	v_permlane32_swap_b32_e32 v219, v0
	v_add_f32_e32 v219, v219, v0
	v_fma_f32 v209, v209, v218, v219
	s_waitcnt vmcnt(0)
	ds_write_b128 v210, v[158:161] offset:43008
	ds_write_b128 v211, v[162:165] offset:51200
	s_waitcnt lgkmcnt(0)
	s_barrier
	global_load_dwordx4 v[158:161], v176, s[18:19]
	global_load_dwordx4 v[162:165], v178, s[16:17]
	v_add_u32_e32 v176, 0x2000, v176
	v_add_u32_e32 v178, 0x20000, v178
	v_max_f32_e32 v177, v114, v115
	v_max3_f32 v177, v177, v116, v117
	v_max3_f32 v177, v177, v118, v119
	v_max3_f32 v177, v177, v120, v121
	v_max3_f32 v177, v177, v122, v123
	v_max3_f32 v177, v177, v124, v125
	v_max3_f32 v177, v177, v126, v127
	v_max3_f32 v177, v177, v128, v129
	s_waitcnt lgkmcnt(6)
	v_mfma_scale_f32_32x32x64_f8f6f4 v[50:65], v[246:253], v[90:97], v[50:65], v194, v194 op_sel_hi:[0,0,0]
	s_waitcnt lgkmcnt(4)
	v_mfma_scale_f32_32x32x64_f8f6f4 v[34:49], v[246:253], v[82:89], v[34:49], v194, v194 op_sel_hi:[0,0,0]
	s_waitcnt lgkmcnt(2)
	v_mfma_scale_f32_32x32x64_f8f6f4 v[18:33], v[246:253], v[74:81], v[18:33], v194, v194 op_sel_hi:[0,0,0]
	s_waitcnt lgkmcnt(0)
	v_mfma_scale_f32_32x32x64_f8f6f4 v[2:17], v[246:253], v[66:73], v[2:17], v194, v194 op_sel_hi:[0,0,0]
	v_max_f32_e32 v0, v98, v99
	v_max3_f32 v0, v0, v100, v101
	v_max3_f32 v0, v0, v102, v103
	v_max3_f32 v0, v0, v104, v105
	v_max3_f32 v0, v0, v106, v107
	v_max3_f32 v0, v0, v108, v109
	v_max3_f32 v0, v0, v110, v111
	v_max3_f32 v0, v0, v112, v113
	v_max_f32_e32 v177, v177, v0
	v_mov_b32_e32 v0, v177
	v_mov_b32_e32 v221, 1.0
	s_nop 0
	v_permlane32_swap_b32_e32 v177, v0
	v_max_f32_e32 v177, v177, v0
	v_cmp_ge_f32_e32 vcc, s90, v177
	s_cmp_eq_u64 vcc, exec
	s_cbranch_scc0 .Lmla_s0_newmax
; __device__ __forceinline__ void finishSM9(f32x16& p0, f32x16& p1, float alpha, float& l_reg, v8i32& p8) {
; #pragma unroll
;   for (int r = 0; r < 16; ++r) { p0[r] = __builtin_amdgcn_exp2f(p0[r]); p1[r] = __builtin_amdgcn_exp2f(p1[r]); }
;   float ps = 0;
; #pragma unroll
;   for (int r = 0; r < 16; ++r) ps += p0[r];
; #pragma unroll
;   for (int r = 0; r < 16; ++r) ps += p1[r];
;   { auto rr = __builtin_amdgcn_permlane32_swap(__float_as_uint(ps), __float_as_uint(ps), false, false);
;     ps = __uint_as_float(rr[0]) + __uint_as_float(rr[1]); }
;   l_reg = l_reg * alpha + ps;
; #pragma unroll
;   for (int g = 0; g < 4; ++g) {
;     int w = __builtin_amdgcn_cvt_pk_fp8_f32(p0[4 * g], p0[4 * g + 1], 0, false); p8[g] = __builtin_amdgcn_cvt_pk_fp8_f32(p0[4 * g + 2], p0[4 * g + 3], w, true);
;     int u = __builtin_amdgcn_cvt_pk_fp8_f32(p1[4 * g], p1[4 * g + 1], 0, false); p8[4 + g] = __builtin_amdgcn_cvt_pk_fp8_f32(p1[4 * g + 2], p1[4 * g + 3], u, true); }
; }
; __device__ __forceinline__ void pv8(f32x16* o, const char* Vt, const v8i32 p8, int r32, int hi) {
;   const int sw = (r32 >> 2) & 3, a0 = r32 * 64 + (((hi * 2) ^ sw) << 4), a1 = r32 * 64 + (((hi * 2 + 1) ^ sw) << 4);
; #pragma unroll
;   for (int d0 = 0; d0 < 4; ++d0) {
;     const v8i32 vf = cat8(*reinterpret_cast<const v4i32*>(Vt + d0 * 2048 + a0), *reinterpret_cast<const v4i32*>(Vt + d0 * 2048 + a1));
;     o[d0] = __builtin_amdgcn_mfma_scale_f32_32x32x64_f8f6f4(p8, vf, o[d0], 0, 0, 0, 127, 0, 127); }
; }
; __device__ __forceinline__ void qkt9(f32x16& p0, f32x16& p1, const char* Kn, const char* Kr, const v8i32* qf, const float init, int r32, int hi) {
; #pragma unroll
;   for (int r = 0; r < 16; ++r) { p0[r] = init; p1[r] = init; }
; #pragma unroll
;   for (int s = 0; s < 2; ++s) { const int c0 = s * 4 + hi * 2;
;     const v8i32 a0 = cat8(*reinterpret_cast<const v4i32*>(Kn + KN8SW(r32, c0)), *reinterpret_cast<const v4i32*>(Kn + KN8SW(r32, c0 + 1)));
;     const v8i32 a1 = cat8(*reinterpret_cast<const v4i32*>(Kn + 4096 + KN8SW(r32, c0)), *reinterpret_cast<const v4i32*>(Kn + 4096 + KN8SW(r32, c0 + 1)));
;     p0 = __builtin_amdgcn_mfma_scale_f32_32x32x64_f8f6f4(a0, qf[s], p0, 0, 0, 0, 127, 0, 124);
;     p1 = __builtin_amdgcn_mfma_scale_f32_32x32x64_f8f6f4(a1, qf[s], p1, 0, 0, 0, 127, 0, 124); }
;   { const int c0 = hi * 2;
.Lmla_s0_cont:
	ds_read_b128 v[82:85], v215 offset:51200
	ds_read_b128 v[86:89], v216 offset:51200
	ds_read_b128 v[222:225], v215 offset:55296
	ds_read_b128 v[226:229], v216 offset:55296
	v_exp_f32_e32 v0, v114
	v_exp_f32_e32 v177, v115
	v_exp_f32_e32 v179, v116
	v_exp_f32_e32 v254, v117
	v_add_f32_e32 v219, v0, v177
	v_cvt_pk_fp8_f32 v246, v0, v177
	v_add_f32_e32 v219, v179, v219
	v_add_f32_e32 v219, v254, v219
	v_cvt_pk_fp8_f32 v246, v179, v254 op_sel:[0,0,1]
	s_waitcnt lgkmcnt(2)
	v_mfma_scale_f32_32x32x64_f8f6f4 v[82:97], v[82:89], v[146:153], v[230:245], v194, v193 op_sel_hi:[0,0,0]
	v_exp_f32_e32 v0, v118
	v_exp_f32_e32 v177, v119
	v_exp_f32_e32 v179, v120
	v_exp_f32_e32 v254, v121
	v_add_f32_e32 v219, v0, v219
	v_add_f32_e32 v219, v177, v219
	v_cvt_pk_fp8_f32 v247, v0, v177
	v_add_f32_e32 v219, v179, v219
	v_add_f32_e32 v219, v254, v219
	v_cvt_pk_fp8_f32 v247, v179, v254 op_sel:[0,0,1]
	ds_read_b128 v[114:117], v213 offset:51200
	ds_read_b128 v[118:121], v214 offset:51200
	s_waitcnt lgkmcnt(2)
	v_mfma_scale_f32_32x32x64_f8f6f4 v[66:81], v[222:229], v[146:153], v[230:245], v194, v193 op_sel_hi:[0,0,0]
	ds_read_b128 v[222:225], v213 offset:55296
	ds_read_b128 v[226:229], v214 offset:55296
	v_exp_f32_e32 v0, v122
	v_exp_f32_e32 v177, v123
	v_exp_f32_e32 v179, v124
	v_exp_f32_e32 v254, v125
	v_add_f32_e32 v219, v0, v219
	v_add_f32_e32 v219, v177, v219
	v_cvt_pk_fp8_f32 v248, v0, v177
	v_add_f32_e32 v219, v179, v219
	v_add_f32_e32 v219, v254, v219
	v_cvt_pk_fp8_f32 v248, v179, v254 op_sel:[0,0,1]
	v_exp_f32_e32 v0, v126
	v_exp_f32_e32 v177, v127
	v_exp_f32_e32 v179, v128
	v_exp_f32_e32 v254, v129
	v_add_f32_e32 v219, v0, v219
	v_add_f32_e32 v219, v177, v219
	v_cvt_pk_fp8_f32 v249, v0, v177
	v_add_f32_e32 v219, v179, v219
	v_add_f32_e32 v219, v254, v219
	v_cvt_pk_fp8_f32 v249, v179, v254 op_sel:[0,0,1]
	ds_read_b128 v[122:125], v185 offset:59392
	ds_read_b128 v[126:129], v186 offset:59392
	s_waitcnt lgkmcnt(4)
	v_mfma_scale_f32_32x32x64_f8f6f4 v[82:97], v[114:121], v[138:145], v[82:97], v194, v193 op_sel_hi:[0,0,0]
	v_exp_f32_e32 v0, v98
	v_exp_f32_e32 v177, v99
	v_exp_f32_e32 v179, v100
	v_exp_f32_e32 v254, v101
	v_add_f32_e32 v219, v0, v219
	v_add_f32_e32 v219, v177, v219
	v_cvt_pk_fp8_f32 v250, v0, v177
	v_add_f32_e32 v219, v179, v219
	v_add_f32_e32 v219, v254, v219
	v_cvt_pk_fp8_f32 v250, v179, v254 op_sel:[0,0,1]
	s_waitcnt lgkmcnt(2)
	v_mfma_scale_f32_32x32x64_f8f6f4 v[66:81], v[222:229], v[138:145], v[66:81], v194, v193 op_sel_hi:[0,0,0]
	ds_read_b128 v[222:225], v185 offset:61440
	ds_read_b128 v[226:229], v186 offset:61440
	v_exp_f32_e32 v0, v102
	v_exp_f32_e32 v177, v103
	v_exp_f32_e32 v179, v104
	v_exp_f32_e32 v254, v105
	v_add_f32_e32 v219, v0, v219
	v_add_f32_e32 v219, v177, v219
	v_cvt_pk_fp8_f32 v251, v0, v177
	v_add_f32_e32 v219, v179, v219
	v_add_f32_e32 v219, v254, v219
	v_cvt_pk_fp8_f32 v251, v179, v254 op_sel:[0,0,1]
	v_exp_f32_e32 v0, v106
	v_exp_f32_e32 v177, v107
	v_exp_f32_e32 v179, v108
	v_exp_f32_e32 v254, v109
	v_add_f32_e32 v219, v0, v219
	v_add_f32_e32 v219, v177, v219
	v_cvt_pk_fp8_f32 v252, v0, v177
	v_add_f32_e32 v219, v179, v219
	v_add_f32_e32 v219, v254, v219
	v_cvt_pk_fp8_f32 v252, v179, v254 op_sel:[0,0,1]
	s_waitcnt lgkmcnt(2)
	v_mfma_scale_f32_32x32x64_f8f6f4 v[82:97], v[122:129], v[130:137], v[82:97], v194, v193 op_sel_hi:[0,0,0]
	v_exp_f32_e32 v0, v110
	v_exp_f32_e32 v177, v111
	v_exp_f32_e32 v179, v112
	v_exp_f32_e32 v254, v113
	v_add_f32_e32 v219, v0, v219
	v_add_f32_e32 v219, v177, v219
	v_cvt_pk_fp8_f32 v253, v0, v177
	v_add_f32_e32 v219, v179, v219
	v_add_f32_e32 v219, v254, v219
	v_cvt_pk_fp8_f32 v253, v179, v254 op_sel:[0,0,1]
	ds_read_b128 v[122:125], v185 offset:8192
	ds_read_b128 v[126:129], v186 offset:8192
	ds_read_b128 v[114:117], v185 offset:10240
	ds_read_b128 v[118:121], v186 offset:10240
	ds_read_b128 v[106:109], v185 offset:12288
	ds_read_b128 v[110:113], v186 offset:12288
	ds_read_b128 v[98:101], v185 offset:14336
	ds_read_b128 v[102:105], v186 offset:14336
	s_waitcnt lgkmcnt(8)
	v_mfma_scale_f32_32x32x64_f8f6f4 v[66:81], v[222:229], v[130:137], v[66:81], v194, v193 op_sel_hi:[0,0,0]
	v_mov_b32_e32 v0, v219
	s_nop 1
	v_permlane32_swap_b32_e32 v219, v0
	v_add_f32_e32 v219, v219, v0
	v_fma_f32 v209, v209, v221, v219
	s_waitcnt vmcnt(0)
	ds_write_b128 v210, v[158:161]
	ds_write_b128 v211, v[162:165] offset:16384
	s_waitcnt lgkmcnt(0)
	s_barrier
	global_load_dwordx4 v[158:161], v176, s[18:19]
	global_load_dwordx4 v[162:165], v178, s[16:17]
	v_add_u32_e32 v176, 0x2000, v176
	v_add_u32_e32 v178, 0x20000, v178
	v_max_f32_e32 v177, v82, v83
	v_max3_f32 v177, v177, v84, v85
	v_max3_f32 v177, v177, v86, v87
	v_max3_f32 v177, v177, v88, v89
	v_max3_f32 v177, v177, v90, v91
	v_max3_f32 v177, v177, v92, v93
	v_max3_f32 v177, v177, v94, v95
	v_max3_f32 v177, v177, v96, v97
	s_waitcnt lgkmcnt(6)
	v_mfma_scale_f32_32x32x64_f8f6f4 v[50:65], v[246:253], v[122:129], v[50:65], v194, v194 op_sel_hi:[0,0,0]
	s_waitcnt lgkmcnt(4)
	v_mfma_scale_f32_32x32x64_f8f6f4 v[34:49], v[246:253], v[114:121], v[34:49], v194, v194 op_sel_hi:[0,0,0]
	s_waitcnt lgkmcnt(2)
	v_mfma_scale_f32_32x32x64_f8f6f4 v[18:33], v[246:253], v[106:113], v[18:33], v194, v194 op_sel_hi:[0,0,0]
	s_waitcnt lgkmcnt(0)
	v_mfma_scale_f32_32x32x64_f8f6f4 v[2:17], v[246:253], v[98:105], v[2:17], v194, v194 op_sel_hi:[0,0,0]
	v_max_f32_e32 v0, v66, v67
	v_max3_f32 v0, v0, v68, v69
	v_max3_f32 v0, v0, v70, v71
	v_max3_f32 v0, v0, v72, v73
	v_max3_f32 v0, v0, v74, v75
	v_max3_f32 v0, v0, v76, v77
	v_max3_f32 v0, v0, v78, v79
	v_max3_f32 v0, v0, v80, v81
	v_max_f32_e32 v177, v177, v0
	v_mov_b32_e32 v0, v177
	v_mov_b32_e32 v218, 1.0
	s_nop 0
	v_permlane32_swap_b32_e32 v177, v0
	v_max_f32_e32 v177, v177, v0
	v_cmp_ge_f32_e32 vcc, s90, v177
	s_cmp_eq_u64 vcc, exec
	s_cbranch_scc0 .Lmla_s1_newmax
; __device__ __forceinline__ void finishSM9(f32x16& p0, f32x16& p1, float alpha, float& l_reg, v8i32& p8) {
; #pragma unroll
;   for (int r = 0; r < 16; ++r) { p0[r] = __builtin_amdgcn_exp2f(p0[r]); p1[r] = __builtin_amdgcn_exp2f(p1[r]); }
;   float ps = 0;
; #pragma unroll
;   for (int r = 0; r < 16; ++r) ps += p0[r];
; #pragma unroll
;   for (int r = 0; r < 16; ++r) ps += p1[r];
;   { auto rr = __builtin_amdgcn_permlane32_swap(__float_as_uint(ps), __float_as_uint(ps), false, false);
;     ps = __uint_as_float(rr[0]) + __uint_as_float(rr[1]); }
;   l_reg = l_reg * alpha + ps;
; #pragma unroll
;   for (int g = 0; g < 4; ++g) {
;     int w = __builtin_amdgcn_cvt_pk_fp8_f32(p0[4 * g], p0[4 * g + 1], 0, false); p8[g] = __builtin_amdgcn_cvt_pk_fp8_f32(p0[4 * g + 2], p0[4 * g + 3], w, true);
;     int u = __builtin_amdgcn_cvt_pk_fp8_f32(p1[4 * g], p1[4 * g + 1], 0, false); p8[4 + g] = __builtin_amdgcn_cvt_pk_fp8_f32(p1[4 * g + 2], p1[4 * g + 3], u, true); }
; }
; __device__ __forceinline__ void pv8(f32x16* o, const char* Vt, const v8i32 p8, int r32, int hi) {
;   const int sw = (r32 >> 2) & 3, a0 = r32 * 64 + (((hi * 2) ^ sw) << 4), a1 = r32 * 64 + (((hi * 2 + 1) ^ sw) << 4);
; #pragma unroll
;   for (int d0 = 0; d0 < 4; ++d0) {
;     const v8i32 vf = cat8(*reinterpret_cast<const v4i32*>(Vt + d0 * 2048 + a0), *reinterpret_cast<const v4i32*>(Vt + d0 * 2048 + a1));
;     o[d0] = __builtin_amdgcn_mfma_scale_f32_32x32x64_f8f6f4(p8, vf, o[d0], 0, 0, 0, 127, 0, 127); }
; }
; __device__ __forceinline__ void qkt9(f32x16& p0, f32x16& p1, const char* Kn, const char* Kr, const v8i32* qf, const float init, int r32, int hi) {
; #pragma unroll
;   for (int r = 0; r < 16; ++r) { p0[r] = init; p1[r] = init; }
; #pragma unroll
;   for (int s = 0; s < 2; ++s) { const int c0 = s * 4 + hi * 2;
;     const v8i32 a0 = cat8(*reinterpret_cast<const v4i32*>(Kn + KN8SW(r32, c0)), *reinterpret_cast<const v4i32*>(Kn + KN8SW(r32, c0 + 1)));
;     const v8i32 a1 = cat8(*reinterpret_cast<const v4i32*>(Kn + 4096 + KN8SW(r32, c0)), *reinterpret_cast<const v4i32*>(Kn + 4096 + KN8SW(r32, c0 + 1)));
;     p0 = __builtin_amdgcn_mfma_scale_f32_32x32x64_f8f6f4(a0, qf[s], p0, 0, 0, 0, 127, 0, 124);
;     p1 = __builtin_amdgcn_mfma_scale_f32_32x32x64_f8f6f4(a1, qf[s], p1, 0, 0, 0, 127, 0, 124); }
;   { const int c0 = hi * 2;
.Lmla_s1_cont:
	ds_read_b128 v[114:117], v215 offset:16384
	ds_read_b128 v[118:121], v216 offset:16384
	ds_read_b128 v[222:225], v215 offset:20480
	ds_read_b128 v[226:229], v216 offset:20480
	v_exp_f32_e32 v0, v82
	v_exp_f32_e32 v177, v83
	v_exp_f32_e32 v179, v84
	v_exp_f32_e32 v254, v85
	v_add_f32_e32 v219, v0, v177
	v_cvt_pk_fp8_f32 v246, v0, v177
	v_add_f32_e32 v219, v179, v219
	v_add_f32_e32 v219, v254, v219
	v_cvt_pk_fp8_f32 v246, v179, v254 op_sel:[0,0,1]
	s_waitcnt lgkmcnt(2)
	v_mfma_scale_f32_32x32x64_f8f6f4 v[114:129], v[114:121], v[146:153], v[230:245], v194, v193 op_sel_hi:[0,0,0]
	v_exp_f32_e32 v0, v86
	v_exp_f32_e32 v177, v87
	v_exp_f32_e32 v179, v88
	v_exp_f32_e32 v254, v89
	v_add_f32_e32 v219, v0, v219
	v_add_f32_e32 v219, v177, v219
	v_cvt_pk_fp8_f32 v247, v0, v177
	v_add_f32_e32 v219, v179, v219
	v_add_f32_e32 v219, v254, v219
	v_cvt_pk_fp8_f32 v247, v179, v254 op_sel:[0,0,1]
	ds_read_b128 v[82:85], v213 offset:16384
	ds_read_b128 v[86:89], v214 offset:16384
	s_waitcnt lgkmcnt(2)
	v_mfma_scale_f32_32x32x64_f8f6f4 v[98:113], v[222:229], v[146:153], v[230:245], v194, v193 op_sel_hi:[0,0,0]
	ds_read_b128 v[222:225], v213 offset:20480
	ds_read_b128 v[226:229], v214 offset:20480
	v_exp_f32_e32 v0, v90
	v_exp_f32_e32 v177, v91
	v_exp_f32_e32 v179, v92
	v_exp_f32_e32 v254, v93
	v_add_f32_e32 v219, v0, v219
	v_add_f32_e32 v219, v177, v219
	v_cvt_pk_fp8_f32 v248, v0, v177
	v_add_f32_e32 v219, v179, v219
	v_add_f32_e32 v219, v254, v219
	v_cvt_pk_fp8_f32 v248, v179, v254 op_sel:[0,0,1]
	v_exp_f32_e32 v0, v94
	v_exp_f32_e32 v177, v95
	v_exp_f32_e32 v179, v96
	v_exp_f32_e32 v254, v97
	v_add_f32_e32 v219, v0, v219
	v_add_f32_e32 v219, v177, v219
	v_cvt_pk_fp8_f32 v249, v0, v177
	v_add_f32_e32 v219, v179, v219
	v_add_f32_e32 v219, v254, v219
	v_cvt_pk_fp8_f32 v249, v179, v254 op_sel:[0,0,1]
	ds_read_b128 v[90:93], v185 offset:32768
	ds_read_b128 v[94:97], v186 offset:32768
	s_waitcnt lgkmcnt(4)
	v_mfma_scale_f32_32x32x64_f8f6f4 v[114:129], v[82:89], v[138:145], v[114:129], v194, v193 op_sel_hi:[0,0,0]
	v_exp_f32_e32 v0, v66
	v_exp_f32_e32 v177, v67
	v_exp_f32_e32 v179, v68
	v_exp_f32_e32 v254, v69
	v_add_f32_e32 v219, v0, v219
	v_add_f32_e32 v219, v177, v219
	v_cvt_pk_fp8_f32 v250, v0, v177
	v_add_f32_e32 v219, v179, v219
	v_add_f32_e32 v219, v254, v219
	v_cvt_pk_fp8_f32 v250, v179, v254 op_sel:[0,0,1]
	s_waitcnt lgkmcnt(2)
	v_mfma_scale_f32_32x32x64_f8f6f4 v[98:113], v[222:229], v[138:145], v[98:113], v194, v193 op_sel_hi:[0,0,0]
	ds_read_b128 v[222:225], v185 offset:34816
	ds_read_b128 v[226:229], v186 offset:34816
	v_exp_f32_e32 v0, v70
	v_exp_f32_e32 v177, v71
	v_exp_f32_e32 v179, v72
	v_exp_f32_e32 v254, v73
	v_add_f32_e32 v219, v0, v219
	v_add_f32_e32 v219, v177, v219
	v_cvt_pk_fp8_f32 v251, v0, v177
	v_add_f32_e32 v219, v179, v219
	v_add_f32_e32 v219, v254, v219
	v_cvt_pk_fp8_f32 v251, v179, v254 op_sel:[0,0,1]
	v_exp_f32_e32 v0, v74
	v_exp_f32_e32 v177, v75
	v_exp_f32_e32 v179, v76
	v_exp_f32_e32 v254, v77
	v_add_f32_e32 v219, v0, v219
	v_add_f32_e32 v219, v177, v219
	v_cvt_pk_fp8_f32 v252, v0, v177
	v_add_f32_e32 v219, v179, v219
	v_add_f32_e32 v219, v254, v219
	v_cvt_pk_fp8_f32 v252, v179, v254 op_sel:[0,0,1]
	s_waitcnt lgkmcnt(2)
	v_mfma_scale_f32_32x32x64_f8f6f4 v[114:129], v[90:97], v[130:137], v[114:129], v194, v193 op_sel_hi:[0,0,0]
	v_exp_f32_e32 v0, v78
	v_exp_f32_e32 v177, v79
	v_exp_f32_e32 v179, v80
	v_exp_f32_e32 v254, v81
	v_add_f32_e32 v219, v0, v219
	v_add_f32_e32 v219, v177, v219
	v_cvt_pk_fp8_f32 v253, v0, v177
	v_add_f32_e32 v219, v179, v219
	v_add_f32_e32 v219, v254, v219
	v_cvt_pk_fp8_f32 v253, v179, v254 op_sel:[0,0,1]
	ds_read_b128 v[90:93], v185 offset:43008
	ds_read_b128 v[94:97], v186 offset:43008
	ds_read_b128 v[82:85], v185 offset:45056
	ds_read_b128 v[86:89], v186 offset:45056
	ds_read_b128 v[74:77], v185 offset:47104
	ds_read_b128 v[78:81], v186 offset:47104
	ds_read_b128 v[66:69], v185 offset:49152
	ds_read_b128 v[70:73], v186 offset:49152
	s_waitcnt lgkmcnt(8)
	v_mfma_scale_f32_32x32x64_f8f6f4 v[98:113], v[222:229], v[130:137], v[98:113], v194, v193 op_sel_hi:[0,0,0]
	v_mov_b32_e32 v0, v219
	s_nop 1
	v_permlane32_swap_b32_e32 v219, v0
	v_add_f32_e32 v219, v219, v0
	v_fma_f32 v209, v209, v218, v219
	s_waitcnt vmcnt(0)
	ds_write_b128 v210, v[158:161] offset:8192
	ds_write_b128 v211, v[162:165] offset:24576
	s_waitcnt lgkmcnt(0)
	s_barrier
	global_load_dwordx4 v[158:161], v176, s[18:19]
	global_load_dwordx4 v[162:165], v178, s[16:17]
	v_add_u32_e32 v176, 0x2000, v176
	v_add_u32_e32 v178, 0x20000, v178
	v_max_f32_e32 v177, v114, v115
	v_max3_f32 v177, v177, v116, v117
	v_max3_f32 v177, v177, v118, v119
	v_max3_f32 v177, v177, v120, v121
	v_max3_f32 v177, v177, v122, v123
	v_max3_f32 v177, v177, v124, v125
	v_max3_f32 v177, v177, v126, v127
	v_max3_f32 v177, v177, v128, v129
	s_waitcnt lgkmcnt(6)
	v_mfma_scale_f32_32x32x64_f8f6f4 v[50:65], v[246:253], v[90:97], v[50:65], v194, v194 op_sel_hi:[0,0,0]
	s_waitcnt lgkmcnt(4)
	v_mfma_scale_f32_32x32x64_f8f6f4 v[34:49], v[246:253], v[82:89], v[34:49], v194, v194 op_sel_hi:[0,0,0]
	s_waitcnt lgkmcnt(2)
	v_mfma_scale_f32_32x32x64_f8f6f4 v[18:33], v[246:253], v[74:81], v[18:33], v194, v194 op_sel_hi:[0,0,0]
	s_waitcnt lgkmcnt(0)
	v_mfma_scale_f32_32x32x64_f8f6f4 v[2:17], v[246:253], v[66:73], v[2:17], v194, v194 op_sel_hi:[0,0,0]
	v_max_f32_e32 v0, v98, v99
	v_max3_f32 v0, v0, v100, v101
	v_max3_f32 v0, v0, v102, v103
	v_max3_f32 v0, v0, v104, v105
	v_max3_f32 v0, v0, v106, v107
	v_max3_f32 v0, v0, v108, v109
	v_max3_f32 v0, v0, v110, v111
	v_max3_f32 v0, v0, v112, v113
	v_max_f32_e32 v177, v177, v0
	v_mov_b32_e32 v0, v177
	v_mov_b32_e32 v221, 1.0
	s_nop 0
	v_permlane32_swap_b32_e32 v177, v0
	v_max_f32_e32 v177, v177, v0
	v_cmp_ge_f32_e32 vcc, s90, v177
	s_cmp_eq_u64 vcc, exec
	s_cbranch_scc0 .Lmla_s2_newmax
; __device__ __forceinline__ void finishSM9(f32x16& p0, f32x16& p1, float alpha, float& l_reg, v8i32& p8) {
; #pragma unroll
;   for (int r = 0; r < 16; ++r) { p0[r] = __builtin_amdgcn_exp2f(p0[r]); p1[r] = __builtin_amdgcn_exp2f(p1[r]); }
;   float ps = 0;
; #pragma unroll
;   for (int r = 0; r < 16; ++r) ps += p0[r];
; #pragma unroll
;   for (int r = 0; r < 16; ++r) ps += p1[r];
;   { auto rr = __builtin_amdgcn_permlane32_swap(__float_as_uint(ps), __float_as_uint(ps), false, false);
;     ps = __uint_as_float(rr[0]) + __uint_as_float(rr[1]); }
;   l_reg = l_reg * alpha + ps;
; #pragma unroll
;   for (int g = 0; g < 4; ++g) {
;     int w = __builtin_amdgcn_cvt_pk_fp8_f32(p0[4 * g], p0[4 * g + 1], 0, false); p8[g] = __builtin_amdgcn_cvt_pk_fp8_f32(p0[4 * g + 2], p0[4 * g + 3], w, true);
;     int u = __builtin_amdgcn_cvt_pk_fp8_f32(p1[4 * g], p1[4 * g + 1], 0, false); p8[4 + g] = __builtin_amdgcn_cvt_pk_fp8_f32(p1[4 * g + 2], p1[4 * g + 3], u, true); }
; }
; __device__ __forceinline__ void pv8(f32x16* o, const char* Vt, const v8i32 p8, int r32, int hi) {
;   const int sw = (r32 >> 2) & 3, a0 = r32 * 64 + (((hi * 2) ^ sw) << 4), a1 = r32 * 64 + (((hi * 2 + 1) ^ sw) << 4);
; #pragma unroll
;   for (int d0 = 0; d0 < 4; ++d0) {
;     const v8i32 vf = cat8(*reinterpret_cast<const v4i32*>(Vt + d0 * 2048 + a0), *reinterpret_cast<const v4i32*>(Vt + d0 * 2048 + a1));
;     o[d0] = __builtin_amdgcn_mfma_scale_f32_32x32x64_f8f6f4(p8, vf, o[d0], 0, 0, 0, 127, 0, 127); }
; }
; __device__ __forceinline__ void qkt9(f32x16& p0, f32x16& p1, const char* Kn, const char* Kr, const v8i32* qf, const float init, int r32, int hi) {
; #pragma unroll
;   for (int r = 0; r < 16; ++r) { p0[r] = init; p1[r] = init; }
; #pragma unroll
;   for (int s = 0; s < 2; ++s) { const int c0 = s * 4 + hi * 2;
;     const v8i32 a0 = cat8(*reinterpret_cast<const v4i32*>(Kn + KN8SW(r32, c0)), *reinterpret_cast<const v4i32*>(Kn + KN8SW(r32, c0 + 1)));
;     const v8i32 a1 = cat8(*reinterpret_cast<const v4i32*>(Kn + 4096 + KN8SW(r32, c0)), *reinterpret_cast<const v4i32*>(Kn + 4096 + KN8SW(r32, c0 + 1)));
;     p0 = __builtin_amdgcn_mfma_scale_f32_32x32x64_f8f6f4(a0, qf[s], p0, 0, 0, 0, 127, 0, 124);
;     p1 = __builtin_amdgcn_mfma_scale_f32_32x32x64_f8f6f4(a1, qf[s], p1, 0, 0, 0, 127, 0, 124); }
;   { const int c0 = hi * 2;
.Lmla_s2_cont:
	ds_read_b128 v[82:85], v215 offset:24576
	ds_read_b128 v[86:89], v216 offset:24576
	ds_read_b128 v[222:225], v215 offset:28672
	ds_read_b128 v[226:229], v216 offset:28672
	v_exp_f32_e32 v0, v114
	v_exp_f32_e32 v177, v115
	v_exp_f32_e32 v179, v116
	v_exp_f32_e32 v254, v117
	v_add_f32_e32 v219, v0, v177
	v_cvt_pk_fp8_f32 v246, v0, v177
	v_add_f32_e32 v219, v179, v219
	v_add_f32_e32 v219, v254, v219
	v_cvt_pk_fp8_f32 v246, v179, v254 op_sel:[0,0,1]
	s_waitcnt lgkmcnt(2)
	v_mfma_scale_f32_32x32x64_f8f6f4 v[82:97], v[82:89], v[146:153], v[230:245], v194, v193 op_sel_hi:[0,0,0]
	v_exp_f32_e32 v0, v118
	v_exp_f32_e32 v177, v119
	v_exp_f32_e32 v179, v120
	v_exp_f32_e32 v254, v121
	v_add_f32_e32 v219, v0, v219
	v_add_f32_e32 v219, v177, v219
	v_cvt_pk_fp8_f32 v247, v0, v177
	v_add_f32_e32 v219, v179, v219
	v_add_f32_e32 v219, v254, v219
	v_cvt_pk_fp8_f32 v247, v179, v254 op_sel:[0,0,1]
	ds_read_b128 v[114:117], v213 offset:24576
	ds_read_b128 v[118:121], v214 offset:24576
	s_waitcnt lgkmcnt(2)
	v_mfma_scale_f32_32x32x64_f8f6f4 v[66:81], v[222:229], v[146:153], v[230:245], v194, v193 op_sel_hi:[0,0,0]
	ds_read_b128 v[222:225], v213 offset:28672
	ds_read_b128 v[226:229], v214 offset:28672
	v_exp_f32_e32 v0, v122
	v_exp_f32_e32 v177, v123
	v_exp_f32_e32 v179, v124
	v_exp_f32_e32 v254, v125
	v_add_f32_e32 v219, v0, v219
	v_add_f32_e32 v219, v177, v219
	v_cvt_pk_fp8_f32 v248, v0, v177
	v_add_f32_e32 v219, v179, v219
	v_add_f32_e32 v219, v254, v219
	v_cvt_pk_fp8_f32 v248, v179, v254 op_sel:[0,0,1]
	v_exp_f32_e32 v0, v126
	v_exp_f32_e32 v177, v127
	v_exp_f32_e32 v179, v128
	v_exp_f32_e32 v254, v129
	v_add_f32_e32 v219, v0, v219
	v_add_f32_e32 v219, v177, v219
	v_cvt_pk_fp8_f32 v249, v0, v177
	v_add_f32_e32 v219, v179, v219
	v_add_f32_e32 v219, v254, v219
	v_cvt_pk_fp8_f32 v249, v179, v254 op_sel:[0,0,1]
	ds_read_b128 v[122:125], v185 offset:36864
	ds_read_b128 v[126:129], v186 offset:36864
	s_waitcnt lgkmcnt(4)
	v_mfma_scale_f32_32x32x64_f8f6f4 v[82:97], v[114:121], v[138:145], v[82:97], v194, v193 op_sel_hi:[0,0,0]
	v_exp_f32_e32 v0, v98
	v_exp_f32_e32 v177, v99
	v_exp_f32_e32 v179, v100
	v_exp_f32_e32 v254, v101
	v_add_f32_e32 v219, v0, v219
	v_add_f32_e32 v219, v177, v219
	v_cvt_pk_fp8_f32 v250, v0, v177
	v_add_f32_e32 v219, v179, v219
	v_add_f32_e32 v219, v254, v219
	v_cvt_pk_fp8_f32 v250, v179, v254 op_sel:[0,0,1]
	s_waitcnt lgkmcnt(2)
	v_mfma_scale_f32_32x32x64_f8f6f4 v[66:81], v[222:229], v[138:145], v[66:81], v194, v193 op_sel_hi:[0,0,0]
	ds_read_b128 v[222:225], v185 offset:38912
	ds_read_b128 v[226:229], v186 offset:38912
	v_exp_f32_e32 v0, v102
	v_exp_f32_e32 v177, v103
	v_exp_f32_e32 v179, v104
	v_exp_f32_e32 v254, v105
	v_add_f32_e32 v219, v0, v219
	v_add_f32_e32 v219, v177, v219
	v_cvt_pk_fp8_f32 v251, v0, v177
	v_add_f32_e32 v219, v179, v219
	v_add_f32_e32 v219, v254, v219
	v_cvt_pk_fp8_f32 v251, v179, v254 op_sel:[0,0,1]
	v_exp_f32_e32 v0, v106
	v_exp_f32_e32 v177, v107
	v_exp_f32_e32 v179, v108
	v_exp_f32_e32 v254, v109
	v_add_f32_e32 v219, v0, v219
	v_add_f32_e32 v219, v177, v219
	v_cvt_pk_fp8_f32 v252, v0, v177
	v_add_f32_e32 v219, v179, v219
	v_add_f32_e32 v219, v254, v219
	v_cvt_pk_fp8_f32 v252, v179, v254 op_sel:[0,0,1]
	s_waitcnt lgkmcnt(2)
	v_mfma_scale_f32_32x32x64_f8f6f4 v[82:97], v[122:129], v[130:137], v[82:97], v194, v193 op_sel_hi:[0,0,0]
	v_exp_f32_e32 v0, v110
	v_exp_f32_e32 v177, v111
	v_exp_f32_e32 v179, v112
	v_exp_f32_e32 v254, v113
	v_add_f32_e32 v219, v0, v219
	v_add_f32_e32 v219, v177, v219
	v_cvt_pk_fp8_f32 v253, v0, v177
	v_add_f32_e32 v219, v179, v219
	v_add_f32_e32 v219, v254, v219
	v_cvt_pk_fp8_f32 v253, v179, v254 op_sel:[0,0,1]
	ds_read_b128 v[122:125], v185 offset:0
	ds_read_b128 v[126:129], v186 offset:0
	ds_read_b128 v[114:117], v185 offset:2048
	ds_read_b128 v[118:121], v186 offset:2048
	ds_read_b128 v[106:109], v185 offset:4096
	ds_read_b128 v[110:113], v186 offset:4096
	ds_read_b128 v[98:101], v185 offset:6144
	ds_read_b128 v[102:105], v186 offset:6144
	s_waitcnt lgkmcnt(8)
	v_mfma_scale_f32_32x32x64_f8f6f4 v[66:81], v[222:229], v[130:137], v[66:81], v194, v193 op_sel_hi:[0,0,0]
	v_mov_b32_e32 v0, v219
	s_nop 1
	v_permlane32_swap_b32_e32 v219, v0
	v_add_f32_e32 v219, v219, v0
	v_fma_f32 v209, v209, v221, v219
	s_waitcnt vmcnt(0)
	ds_write_b128 v210, v[158:161] offset:43008
	ds_write_b128 v211, v[162:165] offset:51200
	s_waitcnt lgkmcnt(0)
	s_barrier
	global_load_dwordx4 v[158:161], v176, s[18:19]
	global_load_dwordx4 v[162:165], v178, s[16:17]
	v_add_u32_e32 v176, 0x2000, v176
	v_add_u32_e32 v178, 0x20000, v178
	v_max_f32_e32 v177, v82, v83
	v_max3_f32 v177, v177, v84, v85
	v_max3_f32 v177, v177, v86, v87
	v_max3_f32 v177, v177, v88, v89
	v_max3_f32 v177, v177, v90, v91
	v_max3_f32 v177, v177, v92, v93
	v_max3_f32 v177, v177, v94, v95
	v_max3_f32 v177, v177, v96, v97
	s_waitcnt lgkmcnt(6)
	v_mfma_scale_f32_32x32x64_f8f6f4 v[50:65], v[246:253], v[122:129], v[50:65], v194, v194 op_sel_hi:[0,0,0]
	s_waitcnt lgkmcnt(4)
	v_mfma_scale_f32_32x32x64_f8f6f4 v[34:49], v[246:253], v[114:121], v[34:49], v194, v194 op_sel_hi:[0,0,0]
	s_waitcnt lgkmcnt(2)
	v_mfma_scale_f32_32x32x64_f8f6f4 v[18:33], v[246:253], v[106:113], v[18:33], v194, v194 op_sel_hi:[0,0,0]
	s_waitcnt lgkmcnt(0)
	v_mfma_scale_f32_32x32x64_f8f6f4 v[2:17], v[246:253], v[98:105], v[2:17], v194, v194 op_sel_hi:[0,0,0]
	v_max_f32_e32 v0, v66, v67
	v_max3_f32 v0, v0, v68, v69
	v_max3_f32 v0, v0, v70, v71
	v_max3_f32 v0, v0, v72, v73
	v_max3_f32 v0, v0, v74, v75
	v_max3_f32 v0, v0, v76, v77
	v_max3_f32 v0, v0, v78, v79
	v_max3_f32 v0, v0, v80, v81
	v_max_f32_e32 v177, v177, v0
	v_mov_b32_e32 v0, v177
	v_mov_b32_e32 v218, 1.0
	s_nop 0
	v_permlane32_swap_b32_e32 v177, v0
	v_max_f32_e32 v177, v177, v0
	v_cmp_ge_f32_e32 vcc, s90, v177
	s_cmp_eq_u64 vcc, exec
	s_cbranch_scc0 .Lmla_s3_newmax
; __device__ __forceinline__ void finishSM9(f32x16& p0, f32x16& p1, float alpha, float& l_reg, v8i32& p8) {
; #pragma unroll
;   for (int r = 0; r < 16; ++r) { p0[r] = __builtin_amdgcn_exp2f(p0[r]); p1[r] = __builtin_amdgcn_exp2f(p1[r]); }
;   float ps = 0;
; #pragma unroll
;   for (int r = 0; r < 16; ++r) ps += p0[r];
; #pragma unroll
;   for (int r = 0; r < 16; ++r) ps += p1[r];
;   { auto rr = __builtin_amdgcn_permlane32_swap(__float_as_uint(ps), __float_as_uint(ps), false, false);
;     ps = __uint_as_float(rr[0]) + __uint_as_float(rr[1]); }
;   l_reg = l_reg * alpha + ps;
; #pragma unroll
;   for (int g = 0; g < 4; ++g) {
;     int w = __builtin_amdgcn_cvt_pk_fp8_f32(p0[4 * g], p0[4 * g + 1], 0, false); p8[g] = __builtin_amdgcn_cvt_pk_fp8_f32(p0[4 * g + 2], p0[4 * g + 3], w, true);
;     int u = __builtin_amdgcn_cvt_pk_fp8_f32(p1[4 * g], p1[4 * g + 1], 0, false); p8[4 + g] = __builtin_amdgcn_cvt_pk_fp8_f32(p1[4 * g + 2], p1[4 * g + 3], u, true); }
; }
; __device__ __forceinline__ void pv8(f32x16* o, const char* Vt, const v8i32 p8, int r32, int hi) {
;   const int sw = (r32 >> 2) & 3, a0 = r32 * 64 + (((hi * 2) ^ sw) << 4), a1 = r32 * 64 + (((hi * 2 + 1) ^ sw) << 4);
; #pragma unroll
;   for (int d0 = 0; d0 < 4; ++d0) {
;     const v8i32 vf = cat8(*reinterpret_cast<const v4i32*>(Vt + d0 * 2048 + a0), *reinterpret_cast<const v4i32*>(Vt + d0 * 2048 + a1));
;     o[d0] = __builtin_amdgcn_mfma_scale_f32_32x32x64_f8f6f4(p8, vf, o[d0], 0, 0, 0, 127, 0, 127); }
; }
; __device__ __forceinline__ void qkt9(f32x16& p0, f32x16& p1, const char* Kn, const char* Kr, const v8i32* qf, const float init, int r32, int hi) {
; #pragma unroll
;   for (int r = 0; r < 16; ++r) { p0[r] = init; p1[r] = init; }
; #pragma unroll
;   for (int s = 0; s < 2; ++s) { const int c0 = s * 4 + hi * 2;
;     const v8i32 a0 = cat8(*reinterpret_cast<const v4i32*>(Kn + KN8SW(r32, c0)), *reinterpret_cast<const v4i32*>(Kn + KN8SW(r32, c0 + 1)));
;     const v8i32 a1 = cat8(*reinterpret_cast<const v4i32*>(Kn + 4096 + KN8SW(r32, c0)), *reinterpret_cast<const v4i32*>(Kn + 4096 + KN8SW(r32, c0 + 1)));
;     p0 = __builtin_amdgcn_mfma_scale_f32_32x32x64_f8f6f4(a0, qf[s], p0, 0, 0, 0, 127, 0, 124);
;     p1 = __builtin_amdgcn_mfma_scale_f32_32x32x64_f8f6f4(a1, qf[s], p1, 0, 0, 0, 127, 0, 124); }
;   { const int c0 = hi * 2;
.Lmla_s3_cont:
	ds_read_b128 v[114:117], v215 offset:51200
	ds_read_b128 v[118:121], v216 offset:51200
	ds_read_b128 v[222:225], v215 offset:55296
	ds_read_b128 v[226:229], v216 offset:55296
	v_exp_f32_e32 v0, v82
	v_exp_f32_e32 v177, v83
	v_exp_f32_e32 v179, v84
	v_exp_f32_e32 v254, v85
	v_add_f32_e32 v219, v0, v177
	v_cvt_pk_fp8_f32 v246, v0, v177
	v_add_f32_e32 v219, v179, v219
	v_add_f32_e32 v219, v254, v219
	v_cvt_pk_fp8_f32 v246, v179, v254 op_sel:[0,0,1]
	s_waitcnt lgkmcnt(2)
	v_mfma_scale_f32_32x32x64_f8f6f4 v[114:129], v[114:121], v[146:153], v[230:245], v194, v193 op_sel_hi:[0,0,0]
	v_exp_f32_e32 v0, v86
	v_exp_f32_e32 v177, v87
	v_exp_f32_e32 v179, v88
	v_exp_f32_e32 v254, v89
	v_add_f32_e32 v219, v0, v219
	v_add_f32_e32 v219, v177, v219
	v_cvt_pk_fp8_f32 v247, v0, v177
	v_add_f32_e32 v219, v179, v219
	v_add_f32_e32 v219, v254, v219
	v_cvt_pk_fp8_f32 v247, v179, v254 op_sel:[0,0,1]
	ds_read_b128 v[82:85], v213 offset:51200
	ds_read_b128 v[86:89], v214 offset:51200
	s_waitcnt lgkmcnt(2)
	v_mfma_scale_f32_32x32x64_f8f6f4 v[98:113], v[222:229], v[146:153], v[230:245], v194, v193 op_sel_hi:[0,0,0]
	ds_read_b128 v[222:225], v213 offset:55296
	ds_read_b128 v[226:229], v214 offset:55296
	v_exp_f32_e32 v0, v90
	v_exp_f32_e32 v177, v91
	v_exp_f32_e32 v179, v92
	v_exp_f32_e32 v254, v93
	v_add_f32_e32 v219, v0, v219
	v_add_f32_e32 v219, v177, v219
	v_cvt_pk_fp8_f32 v248, v0, v177
	v_add_f32_e32 v219, v179, v219
	v_add_f32_e32 v219, v254, v219
	v_cvt_pk_fp8_f32 v248, v179, v254 op_sel:[0,0,1]
	v_exp_f32_e32 v0, v94
	v_exp_f32_e32 v177, v95
	v_exp_f32_e32 v179, v96
	v_exp_f32_e32 v254, v97
	v_add_f32_e32 v219, v0, v219
	v_add_f32_e32 v219, v177, v219
	v_cvt_pk_fp8_f32 v249, v0, v177
	v_add_f32_e32 v219, v179, v219
	v_add_f32_e32 v219, v254, v219
	v_cvt_pk_fp8_f32 v249, v179, v254 op_sel:[0,0,1]
	ds_read_b128 v[90:93], v185 offset:59392
	ds_read_b128 v[94:97], v186 offset:59392
	s_waitcnt lgkmcnt(4)
	v_mfma_scale_f32_32x32x64_f8f6f4 v[114:129], v[82:89], v[138:145], v[114:129], v194, v193 op_sel_hi:[0,0,0]
	v_exp_f32_e32 v0, v66
	v_exp_f32_e32 v177, v67
	v_exp_f32_e32 v179, v68
	v_exp_f32_e32 v254, v69
	v_add_f32_e32 v219, v0, v219
	v_add_f32_e32 v219, v177, v219
	v_cvt_pk_fp8_f32 v250, v0, v177
	v_add_f32_e32 v219, v179, v219
	v_add_f32_e32 v219, v254, v219
	v_cvt_pk_fp8_f32 v250, v179, v254 op_sel:[0,0,1]
	s_waitcnt lgkmcnt(2)
	v_mfma_scale_f32_32x32x64_f8f6f4 v[98:113], v[222:229], v[138:145], v[98:113], v194, v193 op_sel_hi:[0,0,0]
	ds_read_b128 v[222:225], v185 offset:61440
	ds_read_b128 v[226:229], v186 offset:61440
	v_exp_f32_e32 v0, v70
	v_exp_f32_e32 v177, v71
	v_exp_f32_e32 v179, v72
	v_exp_f32_e32 v254, v73
	v_add_f32_e32 v219, v0, v219
	v_add_f32_e32 v219, v177, v219
	v_cvt_pk_fp8_f32 v251, v0, v177
	v_add_f32_e32 v219, v179, v219
	v_add_f32_e32 v219, v254, v219
	v_cvt_pk_fp8_f32 v251, v179, v254 op_sel:[0,0,1]
	v_exp_f32_e32 v0, v74
	v_exp_f32_e32 v177, v75
	v_exp_f32_e32 v179, v76
	v_exp_f32_e32 v254, v77
	v_add_f32_e32 v219, v0, v219
	v_add_f32_e32 v219, v177, v219
	v_cvt_pk_fp8_f32 v252, v0, v177
	v_add_f32_e32 v219, v179, v219
	v_add_f32_e32 v219, v254, v219
	v_cvt_pk_fp8_f32 v252, v179, v254 op_sel:[0,0,1]
	s_waitcnt lgkmcnt(2)
	v_mfma_scale_f32_32x32x64_f8f6f4 v[114:129], v[90:97], v[130:137], v[114:129], v194, v193 op_sel_hi:[0,0,0]
	v_exp_f32_e32 v0, v78
	v_exp_f32_e32 v177, v79
	v_exp_f32_e32 v179, v80
	v_exp_f32_e32 v254, v81
	v_add_f32_e32 v219, v0, v219
	v_add_f32_e32 v219, v177, v219
	v_cvt_pk_fp8_f32 v253, v0, v177
	v_add_f32_e32 v219, v179, v219
	v_add_f32_e32 v219, v254, v219
	v_cvt_pk_fp8_f32 v253, v179, v254 op_sel:[0,0,1]
	ds_read_b128 v[90:93], v185 offset:8192
	ds_read_b128 v[94:97], v186 offset:8192
	ds_read_b128 v[82:85], v185 offset:10240
	ds_read_b128 v[86:89], v186 offset:10240
	ds_read_b128 v[74:77], v185 offset:12288
	ds_read_b128 v[78:81], v186 offset:12288
	ds_read_b128 v[66:69], v185 offset:14336
	ds_read_b128 v[70:73], v186 offset:14336
	s_waitcnt lgkmcnt(8)
	v_mfma_scale_f32_32x32x64_f8f6f4 v[98:113], v[222:229], v[130:137], v[98:113], v194, v193 op_sel_hi:[0,0,0]
	v_mov_b32_e32 v0, v219
	s_nop 1
	v_permlane32_swap_b32_e32 v219, v0
	v_add_f32_e32 v219, v219, v0
	v_fma_f32 v209, v209, v218, v219
	s_waitcnt vmcnt(0)
	ds_write_b128 v210, v[158:161]
	ds_write_b128 v211, v[162:165] offset:16384
	s_waitcnt lgkmcnt(0)
	s_barrier
	global_load_dwordx4 v[158:161], v176, s[18:19]
	global_load_dwordx4 v[162:165], v178, s[16:17]
	v_add_u32_e32 v176, 0x2000, v176
	v_add_u32_e32 v178, 0x20000, v178
	v_max_f32_e32 v177, v114, v115
	v_max3_f32 v177, v177, v116, v117
	v_max3_f32 v177, v177, v118, v119
	v_max3_f32 v177, v177, v120, v121
	v_max3_f32 v177, v177, v122, v123
	v_max3_f32 v177, v177, v124, v125
	v_max3_f32 v177, v177, v126, v127
	v_max3_f32 v177, v177, v128, v129
	s_waitcnt lgkmcnt(6)
	v_mfma_scale_f32_32x32x64_f8f6f4 v[50:65], v[246:253], v[90:97], v[50:65], v194, v194 op_sel_hi:[0,0,0]
	s_waitcnt lgkmcnt(4)
	v_mfma_scale_f32_32x32x64_f8f6f4 v[34:49], v[246:253], v[82:89], v[34:49], v194, v194 op_sel_hi:[0,0,0]
	s_waitcnt lgkmcnt(2)
	v_mfma_scale_f32_32x32x64_f8f6f4 v[18:33], v[246:253], v[74:81], v[18:33], v194, v194 op_sel_hi:[0,0,0]
	s_waitcnt lgkmcnt(0)
	v_mfma_scale_f32_32x32x64_f8f6f4 v[2:17], v[246:253], v[66:73], v[2:17], v194, v194 op_sel_hi:[0,0,0]
	v_max_f32_e32 v0, v98, v99
	v_max3_f32 v0, v0, v100, v101
	v_max3_f32 v0, v0, v102, v103
	v_max3_f32 v0, v0, v104, v105
	v_max3_f32 v0, v0, v106, v107
	v_max3_f32 v0, v0, v108, v109
	v_max3_f32 v0, v0, v110, v111
	v_max3_f32 v0, v0, v112, v113
	v_max_f32_e32 v177, v177, v0
	v_mov_b32_e32 v0, v177
	v_mov_b32_e32 v221, 1.0
	s_nop 0
	v_permlane32_swap_b32_e32 v177, v0
	v_max_f32_e32 v177, v177, v0
	v_cmp_ge_f32_e32 vcc, s90, v177
	s_cmp_eq_u64 vcc, exec
	s_cbranch_scc0 .Lmla_s4_newmax
; __device__ __forceinline__ void finishSM9(f32x16& p0, f32x16& p1, float alpha, float& l_reg, v8i32& p8) {
; #pragma unroll
;   for (int r = 0; r < 16; ++r) { p0[r] = __builtin_amdgcn_exp2f(p0[r]); p1[r] = __builtin_amdgcn_exp2f(p1[r]); }
;   float ps = 0;
; #pragma unroll
;   for (int r = 0; r < 16; ++r) ps += p0[r];
; #pragma unroll
;   for (int r = 0; r < 16; ++r) ps += p1[r];
;   { auto rr = __builtin_amdgcn_permlane32_swap(__float_as_uint(ps), __float_as_uint(ps), false, false);
;     ps = __uint_as_float(rr[0]) + __uint_as_float(rr[1]); }
;   l_reg = l_reg * alpha + ps;
; #pragma unroll
;   for (int g = 0; g < 4; ++g) {
;     int w = __builtin_amdgcn_cvt_pk_fp8_f32(p0[4 * g], p0[4 * g + 1], 0, false); p8[g] = __builtin_amdgcn_cvt_pk_fp8_f32(p0[4 * g + 2], p0[4 * g + 3], w, true);
;     int u = __builtin_amdgcn_cvt_pk_fp8_f32(p1[4 * g], p1[4 * g + 1], 0, false); p8[4 + g] = __builtin_amdgcn_cvt_pk_fp8_f32(p1[4 * g + 2], p1[4 * g + 3], u, true); }
; }
; __device__ __forceinline__ void pv8(f32x16* o, const char* Vt, const v8i32 p8, int r32, int hi) {
;   const int sw = (r32 >> 2) & 3, a0 = r32 * 64 + (((hi * 2) ^ sw) << 4), a1 = r32 * 64 + (((hi * 2 + 1) ^ sw) << 4);
; #pragma unroll
;   for (int d0 = 0; d0 < 4; ++d0) {
;     const v8i32 vf = cat8(*reinterpret_cast<const v4i32*>(Vt + d0 * 2048 + a0), *reinterpret_cast<const v4i32*>(Vt + d0 * 2048 + a1));
;     o[d0] = __builtin_amdgcn_mfma_scale_f32_32x32x64_f8f6f4(p8, vf, o[d0], 0, 0, 0, 127, 0, 127); }
; }
; __device__ __forceinline__ void qkt9(f32x16& p0, f32x16& p1, const char* Kn, const char* Kr, const v8i32* qf, const float init, int r32, int hi) {
; #pragma unroll
;   for (int r = 0; r < 16; ++r) { p0[r] = init; p1[r] = init; }
; #pragma unroll
;   for (int s = 0; s < 2; ++s) { const int c0 = s * 4 + hi * 2;
;     const v8i32 a0 = cat8(*reinterpret_cast<const v4i32*>(Kn + KN8SW(r32, c0)), *reinterpret_cast<const v4i32*>(Kn + KN8SW(r32, c0 + 1)));
;     const v8i32 a1 = cat8(*reinterpret_cast<const v4i32*>(Kn + 4096 + KN8SW(r32, c0)), *reinterpret_cast<const v4i32*>(Kn + 4096 + KN8SW(r32, c0 + 1)));
;     p0 = __builtin_amdgcn_mfma_scale_f32_32x32x64_f8f6f4(a0, qf[s], p0, 0, 0, 0, 127, 0, 124);
;     p1 = __builtin_amdgcn_mfma_scale_f32_32x32x64_f8f6f4(a1, qf[s], p1, 0, 0, 0, 127, 0, 124); }
;   { const int c0 = hi * 2;
.Lmla_s4_cont:
	ds_read_b128 v[82:85], v215 offset:16384
	ds_read_b128 v[86:89], v216 offset:16384
	ds_read_b128 v[222:225], v215 offset:20480
	ds_read_b128 v[226:229], v216 offset:20480
	v_exp_f32_e32 v0, v114
	v_exp_f32_e32 v177, v115
	v_exp_f32_e32 v179, v116
	v_exp_f32_e32 v254, v117
	v_add_f32_e32 v219, v0, v177
	v_cvt_pk_fp8_f32 v246, v0, v177
	v_add_f32_e32 v219, v179, v219
	v_add_f32_e32 v219, v254, v219
	v_cvt_pk_fp8_f32 v246, v179, v254 op_sel:[0,0,1]
	s_waitcnt lgkmcnt(2)
	v_mfma_scale_f32_32x32x64_f8f6f4 v[82:97], v[82:89], v[146:153], v[230:245], v194, v193 op_sel_hi:[0,0,0]
	v_exp_f32_e32 v0, v118
	v_exp_f32_e32 v177, v119
	v_exp_f32_e32 v179, v120
	v_exp_f32_e32 v254, v121
	v_add_f32_e32 v219, v0, v219
	v_add_f32_e32 v219, v177, v219
	v_cvt_pk_fp8_f32 v247, v0, v177
	v_add_f32_e32 v219, v179, v219
	v_add_f32_e32 v219, v254, v219
	v_cvt_pk_fp8_f32 v247, v179, v254 op_sel:[0,0,1]
	ds_read_b128 v[114:117], v213 offset:16384
	ds_read_b128 v[118:121], v214 offset:16384
	s_waitcnt lgkmcnt(2)
	v_mfma_scale_f32_32x32x64_f8f6f4 v[66:81], v[222:229], v[146:153], v[230:245], v194, v193 op_sel_hi:[0,0,0]
	ds_read_b128 v[222:225], v213 offset:20480
	ds_read_b128 v[226:229], v214 offset:20480
	v_exp_f32_e32 v0, v122
	v_exp_f32_e32 v177, v123
	v_exp_f32_e32 v179, v124
	v_exp_f32_e32 v254, v125
	v_add_f32_e32 v219, v0, v219
	v_add_f32_e32 v219, v177, v219
	v_cvt_pk_fp8_f32 v248, v0, v177
	v_add_f32_e32 v219, v179, v219
	v_add_f32_e32 v219, v254, v219
	v_cvt_pk_fp8_f32 v248, v179, v254 op_sel:[0,0,1]
	v_exp_f32_e32 v0, v126
	v_exp_f32_e32 v177, v127
	v_exp_f32_e32 v179, v128
	v_exp_f32_e32 v254, v129
	v_add_f32_e32 v219, v0, v219
	v_add_f32_e32 v219, v177, v219
	v_cvt_pk_fp8_f32 v249, v0, v177
	v_add_f32_e32 v219, v179, v219
	v_add_f32_e32 v219, v254, v219
	v_cvt_pk_fp8_f32 v249, v179, v254 op_sel:[0,0,1]
	ds_read_b128 v[122:125], v185 offset:32768
	ds_read_b128 v[126:129], v186 offset:32768
	s_waitcnt lgkmcnt(4)
	v_mfma_scale_f32_32x32x64_f8f6f4 v[82:97], v[114:121], v[138:145], v[82:97], v194, v193 op_sel_hi:[0,0,0]
	v_exp_f32_e32 v0, v98
	v_exp_f32_e32 v177, v99
	v_exp_f32_e32 v179, v100
	v_exp_f32_e32 v254, v101
	v_add_f32_e32 v219, v0, v219
	v_add_f32_e32 v219, v177, v219
	v_cvt_pk_fp8_f32 v250, v0, v177
	v_add_f32_e32 v219, v179, v219
	v_add_f32_e32 v219, v254, v219
	v_cvt_pk_fp8_f32 v250, v179, v254 op_sel:[0,0,1]
	s_waitcnt lgkmcnt(2)
	v_mfma_scale_f32_32x32x64_f8f6f4 v[66:81], v[222:229], v[138:145], v[66:81], v194, v193 op_sel_hi:[0,0,0]
	ds_read_b128 v[222:225], v185 offset:34816
	ds_read_b128 v[226:229], v186 offset:34816
	v_exp_f32_e32 v0, v102
	v_exp_f32_e32 v177, v103
	v_exp_f32_e32 v179, v104
	v_exp_f32_e32 v254, v105
	v_add_f32_e32 v219, v0, v219
	v_add_f32_e32 v219, v177, v219
	v_cvt_pk_fp8_f32 v251, v0, v177
	v_add_f32_e32 v219, v179, v219
	v_add_f32_e32 v219, v254, v219
	v_cvt_pk_fp8_f32 v251, v179, v254 op_sel:[0,0,1]
	v_exp_f32_e32 v0, v106
	v_exp_f32_e32 v177, v107
	v_exp_f32_e32 v179, v108
	v_exp_f32_e32 v254, v109
	v_add_f32_e32 v219, v0, v219
	v_add_f32_e32 v219, v177, v219
	v_cvt_pk_fp8_f32 v252, v0, v177
	v_add_f32_e32 v219, v179, v219
	v_add_f32_e32 v219, v254, v219
	v_cvt_pk_fp8_f32 v252, v179, v254 op_sel:[0,0,1]
	s_waitcnt lgkmcnt(2)
	v_mfma_scale_f32_32x32x64_f8f6f4 v[82:97], v[122:129], v[130:137], v[82:97], v194, v193 op_sel_hi:[0,0,0]
	v_exp_f32_e32 v0, v110
	v_exp_f32_e32 v177, v111
	v_exp_f32_e32 v179, v112
	v_exp_f32_e32 v254, v113
	v_add_f32_e32 v219, v0, v219
	v_add_f32_e32 v219, v177, v219
	v_cvt_pk_fp8_f32 v253, v0, v177
	v_add_f32_e32 v219, v179, v219
	v_add_f32_e32 v219, v254, v219
	v_cvt_pk_fp8_f32 v253, v179, v254 op_sel:[0,0,1]
	ds_read_b128 v[122:125], v185 offset:43008
	ds_read_b128 v[126:129], v186 offset:43008
	ds_read_b128 v[114:117], v185 offset:45056
	ds_read_b128 v[118:121], v186 offset:45056
	ds_read_b128 v[106:109], v185 offset:47104
	ds_read_b128 v[110:113], v186 offset:47104
	ds_read_b128 v[98:101], v185 offset:49152
	ds_read_b128 v[102:105], v186 offset:49152
	s_waitcnt lgkmcnt(8)
	v_mfma_scale_f32_32x32x64_f8f6f4 v[66:81], v[222:229], v[130:137], v[66:81], v194, v193 op_sel_hi:[0,0,0]
	v_mov_b32_e32 v0, v219
	s_nop 1
	v_permlane32_swap_b32_e32 v219, v0
	v_add_f32_e32 v219, v219, v0
	v_fma_f32 v209, v209, v221, v219
	s_waitcnt vmcnt(0)
	ds_write_b128 v210, v[158:161] offset:8192
	ds_write_b128 v211, v[162:165] offset:24576
	s_waitcnt lgkmcnt(0)
	s_barrier
	global_load_dwordx4 v[158:161], v176, s[18:19]
	global_load_dwordx4 v[162:165], v178, s[16:17]
	v_add_u32_e32 v176, 0x2000, v176
	v_add_u32_e32 v178, 0x20000, v178
	v_max_f32_e32 v177, v82, v83
	v_max3_f32 v177, v177, v84, v85
	v_max3_f32 v177, v177, v86, v87
	v_max3_f32 v177, v177, v88, v89
	v_max3_f32 v177, v177, v90, v91
	v_max3_f32 v177, v177, v92, v93
	v_max3_f32 v177, v177, v94, v95
	v_max3_f32 v177, v177, v96, v97
	s_waitcnt lgkmcnt(6)
	v_mfma_scale_f32_32x32x64_f8f6f4 v[50:65], v[246:253], v[122:129], v[50:65], v194, v194 op_sel_hi:[0,0,0]
	s_waitcnt lgkmcnt(4)
	v_mfma_scale_f32_32x32x64_f8f6f4 v[34:49], v[246:253], v[114:121], v[34:49], v194, v194 op_sel_hi:[0,0,0]
	s_waitcnt lgkmcnt(2)
	v_mfma_scale_f32_32x32x64_f8f6f4 v[18:33], v[246:253], v[106:113], v[18:33], v194, v194 op_sel_hi:[0,0,0]
	s_waitcnt lgkmcnt(0)
	v_mfma_scale_f32_32x32x64_f8f6f4 v[2:17], v[246:253], v[98:105], v[2:17], v194, v194 op_sel_hi:[0,0,0]
	v_max_f32_e32 v0, v66, v67
	v_max3_f32 v0, v0, v68, v69
	v_max3_f32 v0, v0, v70, v71
	v_max3_f32 v0, v0, v72, v73
	v_max3_f32 v0, v0, v74, v75
	v_max3_f32 v0, v0, v76, v77
	v_max3_f32 v0, v0, v78, v79
	v_max3_f32 v0, v0, v80, v81
	v_max_f32_e32 v177, v177, v0
	v_mov_b32_e32 v0, v177
	v_mov_b32_e32 v218, 1.0
	s_nop 0
	v_permlane32_swap_b32_e32 v177, v0
	v_max_f32_e32 v177, v177, v0
	v_cmp_ge_f32_e32 vcc, s90, v177
	s_cmp_eq_u64 vcc, exec
	s_cbranch_scc0 .Lmla_s5_newmax
; __device__ __forceinline__ void finishSM9(f32x16& p0, f32x16& p1, float alpha, float& l_reg, v8i32& p8) {
; #pragma unroll
;   for (int r = 0; r < 16; ++r) { p0[r] = __builtin_amdgcn_exp2f(p0[r]); p1[r] = __builtin_amdgcn_exp2f(p1[r]); }
;   float ps = 0;
; #pragma unroll
;   for (int r = 0; r < 16; ++r) ps += p0[r];
; #pragma unroll
;   for (int r = 0; r < 16; ++r) ps += p1[r];
;   { auto rr = __builtin_amdgcn_permlane32_swap(__float_as_uint(ps), __float_as_uint(ps), false, false);
;     ps = __uint_as_float(rr[0]) + __uint_as_float(rr[1]); }
;   l_reg = l_reg * alpha + ps;
; #pragma unroll
;   for (int g = 0; g < 4; ++g) {
;     int w = __builtin_amdgcn_cvt_pk_fp8_f32(p0[4 * g], p0[4 * g + 1], 0, false); p8[g] = __builtin_amdgcn_cvt_pk_fp8_f32(p0[4 * g + 2], p0[4 * g + 3], w, true);
;     int u = __builtin_amdgcn_cvt_pk_fp8_f32(p1[4 * g], p1[4 * g + 1], 0, false); p8[4 + g] = __builtin_amdgcn_cvt_pk_fp8_f32(p1[4 * g + 2], p1[4 * g + 3], u, true); }
; }
; __device__ __forceinline__ void pv8(f32x16* o, const char* Vt, const v8i32 p8, int r32, int hi) {
;   const int sw = (r32 >> 2) & 3, a0 = r32 * 64 + (((hi * 2) ^ sw) << 4), a1 = r32 * 64 + (((hi * 2 + 1) ^ sw) << 4);
; #pragma unroll
;   for (int d0 = 0; d0 < 4; ++d0) {
;     const v8i32 vf = cat8(*reinterpret_cast<const v4i32*>(Vt + d0 * 2048 + a0), *reinterpret_cast<const v4i32*>(Vt + d0 * 2048 + a1));
;     o[d0] = __builtin_amdgcn_mfma_scale_f32_32x32x64_f8f6f4(p8, vf, o[d0], 0, 0, 0, 127, 0, 127); }
; }
; __device__ __forceinline__ void qkt9(f32x16& p0, f32x16& p1, const char* Kn, const char* Kr, const v8i32* qf, const float init, int r32, int hi) {
; #pragma unroll
;   for (int r = 0; r < 16; ++r) { p0[r] = init; p1[r] = init; }
; #pragma unroll
;   for (int s = 0; s < 2; ++s) { const int c0 = s * 4 + hi * 2;
;     const v8i32 a0 = cat8(*reinterpret_cast<const v4i32*>(Kn + KN8SW(r32, c0)), *reinterpret_cast<const v4i32*>(Kn + KN8SW(r32, c0 + 1)));
;     const v8i32 a1 = cat8(*reinterpret_cast<const v4i32*>(Kn + 4096 + KN8SW(r32, c0)), *reinterpret_cast<const v4i32*>(Kn + 4096 + KN8SW(r32, c0 + 1)));
;     p0 = __builtin_amdgcn_mfma_scale_f32_32x32x64_f8f6f4(a0, qf[s], p0, 0, 0, 0, 127, 0, 124);
;     p1 = __builtin_amdgcn_mfma_scale_f32_32x32x64_f8f6f4(a1, qf[s], p1, 0, 0, 0, 127, 0, 124); }
;   { const int c0 = hi * 2;
.Lmla_s5_cont:
	s_add_i32 s30, s30, 1
	s_cmpk_lt_u32 s30, 42
	s_cbranch_scc1 .Lmla_stag_loop
	ds_read_b128 v[114:117], v215 offset:24576
	ds_read_b128 v[118:121], v216 offset:24576
	ds_read_b128 v[222:225], v215 offset:28672
	ds_read_b128 v[226:229], v216 offset:28672
	v_exp_f32_e32 v0, v82
	v_exp_f32_e32 v177, v83
	v_exp_f32_e32 v179, v84
	v_exp_f32_e32 v254, v85
	v_add_f32_e32 v219, v0, v177
	v_cvt_pk_fp8_f32 v246, v0, v177
	v_add_f32_e32 v219, v179, v219
	v_add_f32_e32 v219, v254, v219
	v_cvt_pk_fp8_f32 v246, v179, v254 op_sel:[0,0,1]
	s_waitcnt lgkmcnt(2)
	v_mfma_scale_f32_32x32x64_f8f6f4 v[114:129], v[114:121], v[146:153], v[230:245], v194, v193 op_sel_hi:[0,0,0]
	v_exp_f32_e32 v0, v86
	v_exp_f32_e32 v177, v87
	v_exp_f32_e32 v179, v88
	v_exp_f32_e32 v254, v89
	v_add_f32_e32 v219, v0, v219
	v_add_f32_e32 v219, v177, v219
	v_cvt_pk_fp8_f32 v247, v0, v177
	v_add_f32_e32 v219, v179, v219
	v_add_f32_e32 v219, v254, v219
	v_cvt_pk_fp8_f32 v247, v179, v254 op_sel:[0,0,1]
	ds_read_b128 v[82:85], v213 offset:24576
	ds_read_b128 v[86:89], v214 offset:24576
	s_waitcnt lgkmcnt(2)
	v_mfma_scale_f32_32x32x64_f8f6f4 v[98:113], v[222:229], v[146:153], v[230:245], v194, v193 op_sel_hi:[0,0,0]
	ds_read_b128 v[222:225], v213 offset:28672
	ds_read_b128 v[226:229], v214 offset:28672
	v_exp_f32_e32 v0, v90
	v_exp_f32_e32 v177, v91
	v_exp_f32_e32 v179, v92
	v_exp_f32_e32 v254, v93
	v_add_f32_e32 v219, v0, v219
	v_add_f32_e32 v219, v177, v219
	v_cvt_pk_fp8_f32 v248, v0, v177
	v_add_f32_e32 v219, v179, v219
	v_add_f32_e32 v219, v254, v219
	v_cvt_pk_fp8_f32 v248, v179, v254 op_sel:[0,0,1]
	v_exp_f32_e32 v0, v94
	v_exp_f32_e32 v177, v95
	v_exp_f32_e32 v179, v96
	v_exp_f32_e32 v254, v97
	v_add_f32_e32 v219, v0, v219
	v_add_f32_e32 v219, v177, v219
	v_cvt_pk_fp8_f32 v249, v0, v177
	v_add_f32_e32 v219, v179, v219
	v_add_f32_e32 v219, v254, v219
	v_cvt_pk_fp8_f32 v249, v179, v254 op_sel:[0,0,1]
	ds_read_b128 v[90:93], v185 offset:36864
	ds_read_b128 v[94:97], v186 offset:36864
	s_waitcnt lgkmcnt(4)
	v_mfma_scale_f32_32x32x64_f8f6f4 v[114:129], v[82:89], v[138:145], v[114:129], v194, v193 op_sel_hi:[0,0,0]
	v_exp_f32_e32 v0, v66
	v_exp_f32_e32 v177, v67
	v_exp_f32_e32 v179, v68
	v_exp_f32_e32 v254, v69
	v_add_f32_e32 v219, v0, v219
	v_add_f32_e32 v219, v177, v219
	v_cvt_pk_fp8_f32 v250, v0, v177
	v_add_f32_e32 v219, v179, v219
	v_add_f32_e32 v219, v254, v219
	v_cvt_pk_fp8_f32 v250, v179, v254 op_sel:[0,0,1]
	s_waitcnt lgkmcnt(2)
	v_mfma_scale_f32_32x32x64_f8f6f4 v[98:113], v[222:229], v[138:145], v[98:113], v194, v193 op_sel_hi:[0,0,0]
	ds_read_b128 v[222:225], v185 offset:38912
	ds_read_b128 v[226:229], v186 offset:38912
	v_exp_f32_e32 v0, v70
	v_exp_f32_e32 v177, v71
	v_exp_f32_e32 v179, v72
	v_exp_f32_e32 v254, v73
	v_add_f32_e32 v219, v0, v219
	v_add_f32_e32 v219, v177, v219
	v_cvt_pk_fp8_f32 v251, v0, v177
	v_add_f32_e32 v219, v179, v219
	v_add_f32_e32 v219, v254, v219
	v_cvt_pk_fp8_f32 v251, v179, v254 op_sel:[0,0,1]
	v_exp_f32_e32 v0, v74
	v_exp_f32_e32 v177, v75
	v_exp_f32_e32 v179, v76
	v_exp_f32_e32 v254, v77
	v_add_f32_e32 v219, v0, v219
	v_add_f32_e32 v219, v177, v219
	v_cvt_pk_fp8_f32 v252, v0, v177
	v_add_f32_e32 v219, v179, v219
	v_add_f32_e32 v219, v254, v219
	v_cvt_pk_fp8_f32 v252, v179, v254 op_sel:[0,0,1]
	s_waitcnt lgkmcnt(2)
	v_mfma_scale_f32_32x32x64_f8f6f4 v[114:129], v[90:97], v[130:137], v[114:129], v194, v193 op_sel_hi:[0,0,0]
	v_exp_f32_e32 v0, v78
	v_exp_f32_e32 v177, v79
	v_exp_f32_e32 v179, v80
	v_exp_f32_e32 v254, v81
	v_add_f32_e32 v219, v0, v219
	v_add_f32_e32 v219, v177, v219
	v_cvt_pk_fp8_f32 v253, v0, v177
	v_add_f32_e32 v219, v179, v219
	v_add_f32_e32 v219, v254, v219
	v_cvt_pk_fp8_f32 v253, v179, v254 op_sel:[0,0,1]
	ds_read_b128 v[90:93], v185 offset:0
	ds_read_b128 v[94:97], v186 offset:0
	ds_read_b128 v[82:85], v185 offset:2048
	ds_read_b128 v[86:89], v186 offset:2048
	ds_read_b128 v[74:77], v185 offset:4096
	ds_read_b128 v[78:81], v186 offset:4096
	ds_read_b128 v[66:69], v185 offset:6144
	ds_read_b128 v[70:73], v186 offset:6144
	s_waitcnt lgkmcnt(8)
	v_mfma_scale_f32_32x32x64_f8f6f4 v[98:113], v[222:229], v[130:137], v[98:113], v194, v193 op_sel_hi:[0,0,0]
	v_mov_b32_e32 v0, v219
	s_nop 1
	v_permlane32_swap_b32_e32 v219, v0
	v_add_f32_e32 v219, v219, v0
	v_fma_f32 v209, v209, v218, v219
	s_waitcnt vmcnt(0)
	ds_write_b128 v210, v[158:161] offset:43008
	ds_write_b128 v211, v[162:165] offset:51200
	s_waitcnt lgkmcnt(0)
	s_barrier
	global_load_dwordx4 v[158:161], v176, s[18:19]
	global_load_dwordx4 v[162:165], v178, s[16:17]
	v_add_u32_e32 v176, 0x2000, v176
	v_add_u32_e32 v178, 0x20000, v178
	v_max_f32_e32 v177, v114, v115
	v_max3_f32 v177, v177, v116, v117
	v_max3_f32 v177, v177, v118, v119
	v_max3_f32 v177, v177, v120, v121
	v_max3_f32 v177, v177, v122, v123
	v_max3_f32 v177, v177, v124, v125
	v_max3_f32 v177, v177, v126, v127
	v_max3_f32 v177, v177, v128, v129
	s_waitcnt lgkmcnt(6)
	v_mfma_scale_f32_32x32x64_f8f6f4 v[50:65], v[246:253], v[90:97], v[50:65], v194, v194 op_sel_hi:[0,0,0]
	s_waitcnt lgkmcnt(4)
	v_mfma_scale_f32_32x32x64_f8f6f4 v[34:49], v[246:253], v[82:89], v[34:49], v194, v194 op_sel_hi:[0,0,0]
	s_waitcnt lgkmcnt(2)
	v_mfma_scale_f32_32x32x64_f8f6f4 v[18:33], v[246:253], v[74:81], v[18:33], v194, v194 op_sel_hi:[0,0,0]
	s_waitcnt lgkmcnt(0)
	v_mfma_scale_f32_32x32x64_f8f6f4 v[2:17], v[246:253], v[66:73], v[2:17], v194, v194 op_sel_hi:[0,0,0]
	v_max_f32_e32 v0, v98, v99
	v_max3_f32 v0, v0, v100, v101
	v_max3_f32 v0, v0, v102, v103
	v_max3_f32 v0, v0, v104, v105
	v_max3_f32 v0, v0, v106, v107
	v_max3_f32 v0, v0, v108, v109
	v_max3_f32 v0, v0, v110, v111
	v_max3_f32 v0, v0, v112, v113
	v_max_f32_e32 v177, v177, v0
	v_mov_b32_e32 v0, v177
	v_mov_b32_e32 v221, 1.0
	s_nop 0
	v_permlane32_swap_b32_e32 v177, v0
	v_max_f32_e32 v177, v177, v0
	v_cmp_ge_f32_e32 vcc, s90, v177
	s_cmp_eq_u64 vcc, exec
	s_cbranch_scc0 .Lmla_q0_newmax
; __device__ __forceinline__ void finishSM9(f32x16& p0, f32x16& p1, float alpha, float& l_reg, v8i32& p8) {
; #pragma unroll
;   for (int r = 0; r < 16; ++r) { p0[r] = __builtin_amdgcn_exp2f(p0[r]); p1[r] = __builtin_amdgcn_exp2f(p1[r]); }
;   float ps = 0;
; #pragma unroll
;   for (int r = 0; r < 16; ++r) ps += p0[r];
; #pragma unroll
;   for (int r = 0; r < 16; ++r) ps += p1[r];
;   { auto rr = __builtin_amdgcn_permlane32_swap(__float_as_uint(ps), __float_as_uint(ps), false, false);
;     ps = __uint_as_float(rr[0]) + __uint_as_float(rr[1]); }
;   l_reg = l_reg * alpha + ps;
; #pragma unroll
;   for (int g = 0; g < 4; ++g) {
;     int w = __builtin_amdgcn_cvt_pk_fp8_f32(p0[4 * g], p0[4 * g + 1], 0, false); p8[g] = __builtin_amdgcn_cvt_pk_fp8_f32(p0[4 * g + 2], p0[4 * g + 3], w, true);
;     int u = __builtin_amdgcn_cvt_pk_fp8_f32(p1[4 * g], p1[4 * g + 1], 0, false); p8[4 + g] = __builtin_amdgcn_cvt_pk_fp8_f32(p1[4 * g + 2], p1[4 * g + 3], u, true); }
; }
; __device__ __forceinline__ void pv8(f32x16* o, const char* Vt, const v8i32 p8, int r32, int hi) {
;   const int sw = (r32 >> 2) & 3, a0 = r32 * 64 + (((hi * 2) ^ sw) << 4), a1 = r32 * 64 + (((hi * 2 + 1) ^ sw) << 4);
; #pragma unroll
;   for (int d0 = 0; d0 < 4; ++d0) {
;     const v8i32 vf = cat8(*reinterpret_cast<const v4i32*>(Vt + d0 * 2048 + a0), *reinterpret_cast<const v4i32*>(Vt + d0 * 2048 + a1));
;     o[d0] = __builtin_amdgcn_mfma_scale_f32_32x32x64_f8f6f4(p8, vf, o[d0], 0, 0, 0, 127, 0, 127); }
; }
; __device__ __forceinline__ void qkt9(f32x16& p0, f32x16& p1, const char* Kn, const char* Kr, const v8i32* qf, const float init, int r32, int hi) {
; #pragma unroll
;   for (int r = 0; r < 16; ++r) { p0[r] = init; p1[r] = init; }
; #pragma unroll
;   for (int s = 0; s < 2; ++s) { const int c0 = s * 4 + hi * 2;
;     const v8i32 a0 = cat8(*reinterpret_cast<const v4i32*>(Kn + KN8SW(r32, c0)), *reinterpret_cast<const v4i32*>(Kn + KN8SW(r32, c0 + 1)));
;     const v8i32 a1 = cat8(*reinterpret_cast<const v4i32*>(Kn + 4096 + KN8SW(r32, c0)), *reinterpret_cast<const v4i32*>(Kn + 4096 + KN8SW(r32, c0 + 1)));
;     p0 = __builtin_amdgcn_mfma_scale_f32_32x32x64_f8f6f4(a0, qf[s], p0, 0, 0, 0, 127, 0, 124);
;     p1 = __builtin_amdgcn_mfma_scale_f32_32x32x64_f8f6f4(a1, qf[s], p1, 0, 0, 0, 127, 0, 124); }
;   { const int c0 = hi * 2;
.Lmla_q0_cont:
	ds_read_b128 v[82:85], v215 offset:51200
	ds_read_b128 v[86:89], v216 offset:51200
	ds_read_b128 v[222:225], v215 offset:55296
	ds_read_b128 v[226:229], v216 offset:55296
	v_exp_f32_e32 v0, v114
	v_exp_f32_e32 v177, v115
	v_exp_f32_e32 v179, v116
	v_exp_f32_e32 v254, v117
	v_add_f32_e32 v219, v0, v177
	v_cvt_pk_fp8_f32 v246, v0, v177
	v_add_f32_e32 v219, v179, v219
	v_add_f32_e32 v219, v254, v219
	v_cvt_pk_fp8_f32 v246, v179, v254 op_sel:[0,0,1]
	s_waitcnt lgkmcnt(2)
	v_mfma_scale_f32_32x32x64_f8f6f4 v[82:97], v[82:89], v[146:153], v[230:245], v194, v193 op_sel_hi:[0,0,0]
	v_exp_f32_e32 v0, v118
	v_exp_f32_e32 v177, v119
	v_exp_f32_e32 v179, v120
	v_exp_f32_e32 v254, v121
	v_add_f32_e32 v219, v0, v219
	v_add_f32_e32 v219, v177, v219
	v_cvt_pk_fp8_f32 v247, v0, v177
	v_add_f32_e32 v219, v179, v219
	v_add_f32_e32 v219, v254, v219
	v_cvt_pk_fp8_f32 v247, v179, v254 op_sel:[0,0,1]
	ds_read_b128 v[114:117], v213 offset:51200
	ds_read_b128 v[118:121], v214 offset:51200
	s_waitcnt lgkmcnt(2)
	v_mfma_scale_f32_32x32x64_f8f6f4 v[66:81], v[222:229], v[146:153], v[230:245], v194, v193 op_sel_hi:[0,0,0]
	ds_read_b128 v[222:225], v213 offset:55296
	ds_read_b128 v[226:229], v214 offset:55296
	v_exp_f32_e32 v0, v122
	v_exp_f32_e32 v177, v123
	v_exp_f32_e32 v179, v124
	v_exp_f32_e32 v254, v125
	v_add_f32_e32 v219, v0, v219
	v_add_f32_e32 v219, v177, v219
	v_cvt_pk_fp8_f32 v248, v0, v177
	v_add_f32_e32 v219, v179, v219
	v_add_f32_e32 v219, v254, v219
	v_cvt_pk_fp8_f32 v248, v179, v254 op_sel:[0,0,1]
	v_exp_f32_e32 v0, v126
	v_exp_f32_e32 v177, v127
	v_exp_f32_e32 v179, v128
	v_exp_f32_e32 v254, v129
	v_add_f32_e32 v219, v0, v219
	v_add_f32_e32 v219, v177, v219
	v_cvt_pk_fp8_f32 v249, v0, v177
	v_add_f32_e32 v219, v179, v219
	v_add_f32_e32 v219, v254, v219
	v_cvt_pk_fp8_f32 v249, v179, v254 op_sel:[0,0,1]
	ds_read_b128 v[122:125], v185 offset:59392
	ds_read_b128 v[126:129], v186 offset:59392
	s_waitcnt lgkmcnt(4)
	v_mfma_scale_f32_32x32x64_f8f6f4 v[82:97], v[114:121], v[138:145], v[82:97], v194, v193 op_sel_hi:[0,0,0]
	v_exp_f32_e32 v0, v98
	v_exp_f32_e32 v177, v99
	v_exp_f32_e32 v179, v100
	v_exp_f32_e32 v254, v101
	v_add_f32_e32 v219, v0, v219
	v_add_f32_e32 v219, v177, v219
	v_cvt_pk_fp8_f32 v250, v0, v177
	v_add_f32_e32 v219, v179, v219
	v_add_f32_e32 v219, v254, v219
	v_cvt_pk_fp8_f32 v250, v179, v254 op_sel:[0,0,1]
	s_waitcnt lgkmcnt(2)
	v_mfma_scale_f32_32x32x64_f8f6f4 v[66:81], v[222:229], v[138:145], v[66:81], v194, v193 op_sel_hi:[0,0,0]
	ds_read_b128 v[222:225], v185 offset:61440
	ds_read_b128 v[226:229], v186 offset:61440
	v_exp_f32_e32 v0, v102
	v_exp_f32_e32 v177, v103
	v_exp_f32_e32 v179, v104
	v_exp_f32_e32 v254, v105
	v_add_f32_e32 v219, v0, v219
	v_add_f32_e32 v219, v177, v219
	v_cvt_pk_fp8_f32 v251, v0, v177
	v_add_f32_e32 v219, v179, v219
	v_add_f32_e32 v219, v254, v219
	v_cvt_pk_fp8_f32 v251, v179, v254 op_sel:[0,0,1]
	v_exp_f32_e32 v0, v106
	v_exp_f32_e32 v177, v107
	v_exp_f32_e32 v179, v108
	v_exp_f32_e32 v254, v109
	v_add_f32_e32 v219, v0, v219
	v_add_f32_e32 v219, v177, v219
	v_cvt_pk_fp8_f32 v252, v0, v177
	v_add_f32_e32 v219, v179, v219
	v_add_f32_e32 v219, v254, v219
	v_cvt_pk_fp8_f32 v252, v179, v254 op_sel:[0,0,1]
	s_waitcnt lgkmcnt(2)
	v_mfma_scale_f32_32x32x64_f8f6f4 v[82:97], v[122:129], v[130:137], v[82:97], v194, v193 op_sel_hi:[0,0,0]
	v_exp_f32_e32 v0, v110
	v_exp_f32_e32 v177, v111
	v_exp_f32_e32 v179, v112
	v_exp_f32_e32 v254, v113
	v_add_f32_e32 v219, v0, v219
	v_add_f32_e32 v219, v177, v219
	v_cvt_pk_fp8_f32 v253, v0, v177
	v_add_f32_e32 v219, v179, v219
	v_add_f32_e32 v219, v254, v219
	v_cvt_pk_fp8_f32 v253, v179, v254 op_sel:[0,0,1]
	ds_read_b128 v[122:125], v185 offset:8192
	ds_read_b128 v[126:129], v186 offset:8192
	ds_read_b128 v[114:117], v185 offset:10240
	ds_read_b128 v[118:121], v186 offset:10240
	ds_read_b128 v[106:109], v185 offset:12288
	ds_read_b128 v[110:113], v186 offset:12288
	ds_read_b128 v[98:101], v185 offset:14336
	ds_read_b128 v[102:105], v186 offset:14336
	s_waitcnt lgkmcnt(8)
	v_mfma_scale_f32_32x32x64_f8f6f4 v[66:81], v[222:229], v[130:137], v[66:81], v194, v193 op_sel_hi:[0,0,0]
	v_mov_b32_e32 v0, v219
	s_nop 1
	v_permlane32_swap_b32_e32 v219, v0
	v_add_f32_e32 v219, v219, v0
	v_fma_f32 v209, v209, v221, v219
	s_waitcnt vmcnt(0)
	ds_write_b128 v210, v[158:161]
	ds_write_b128 v211, v[162:165] offset:16384
	s_waitcnt lgkmcnt(0)
	s_barrier
	v_max_f32_e32 v177, v82, v83
	v_max3_f32 v177, v177, v84, v85
	v_max3_f32 v177, v177, v86, v87
	v_max3_f32 v177, v177, v88, v89
	v_max3_f32 v177, v177, v90, v91
	v_max3_f32 v177, v177, v92, v93
	v_max3_f32 v177, v177, v94, v95
	v_max3_f32 v177, v177, v96, v97
	s_waitcnt lgkmcnt(6)
	v_mfma_scale_f32_32x32x64_f8f6f4 v[50:65], v[246:253], v[122:129], v[50:65], v194, v194 op_sel_hi:[0,0,0]
	s_waitcnt lgkmcnt(4)
	v_mfma_scale_f32_32x32x64_f8f6f4 v[34:49], v[246:253], v[114:121], v[34:49], v194, v194 op_sel_hi:[0,0,0]
	s_waitcnt lgkmcnt(2)
	v_mfma_scale_f32_32x32x64_f8f6f4 v[18:33], v[246:253], v[106:113], v[18:33], v194, v194 op_sel_hi:[0,0,0]
	s_waitcnt lgkmcnt(0)
	v_mfma_scale_f32_32x32x64_f8f6f4 v[2:17], v[246:253], v[98:105], v[2:17], v194, v194 op_sel_hi:[0,0,0]
	v_max_f32_e32 v0, v66, v67
	v_max3_f32 v0, v0, v68, v69
	v_max3_f32 v0, v0, v70, v71
	v_max3_f32 v0, v0, v72, v73
	v_max3_f32 v0, v0, v74, v75
	v_max3_f32 v0, v0, v76, v77
	v_max3_f32 v0, v0, v78, v79
	v_max3_f32 v0, v0, v80, v81
	v_max_f32_e32 v177, v177, v0
	v_mov_b32_e32 v0, v177
	v_mov_b32_e32 v218, 1.0
	s_nop 0
	v_permlane32_swap_b32_e32 v177, v0
	v_max_f32_e32 v177, v177, v0
	v_cmp_ge_f32_e32 vcc, s90, v177
	s_cmp_eq_u64 vcc, exec
	s_cbranch_scc0 .Lmla_q1_newmax

; __device__ __forceinline__ void partialSM9(f32x16& p0, f32x16& p1, float& m_run, float& alpha, const float thr2) {
;   float pmax = p0[0];
; #pragma unroll
;   for (int r = 1; r < 16; ++r) pmax = fmaxf(pmax, p0[r]);
; #pragma unroll
;   for (int r = 0; r < 16; ++r) pmax = fmaxf(pmax, p1[r]);
;   { auto rr = __builtin_amdgcn_permlane32_swap(__float_as_uint(pmax), __float_as_uint(pmax), false, false);
;     pmax = fmaxf(__uint_as_float(rr[0]), __uint_as_float(rr[1])); }
;   if (__builtin_expect(__all(pmax <= 7.0f + thr2), 1)) { alpha = 1.f; }
;   else { const float delta = fmaxf(pmax - 7.0f, 0.f); alpha = __builtin_amdgcn_exp2f(-delta); m_run += delta;
; #pragma unroll
;     for (int r = 0; r < 16; ++r) { p0[r] -= delta; p1[r] -= delta; } }
; }
.Lmla_h0_newmax:
	v_add_f32_e32 v0, 0xc0c00000, v177
	v_max_f32_e32 v177, 0, v0
	v_exp_f32_e64 v221, -v177
	v_add_f32_e32 v217, v217, v177
	v_sub_f32_e32 v129, v129, v177
	v_sub_f32_e32 v128, v128, v177
	v_sub_f32_e32 v127, v127, v177
	v_sub_f32_e32 v126, v126, v177
	v_sub_f32_e32 v125, v125, v177
	v_sub_f32_e32 v124, v124, v177
	v_sub_f32_e32 v123, v123, v177
	v_sub_f32_e32 v122, v122, v177
	v_sub_f32_e32 v121, v121, v177
	v_sub_f32_e32 v120, v120, v177
	v_sub_f32_e32 v119, v119, v177
	v_sub_f32_e32 v118, v118, v177
	v_sub_f32_e32 v117, v117, v177
	v_sub_f32_e32 v116, v116, v177
	v_sub_f32_e32 v115, v115, v177
	v_sub_f32_e32 v114, v114, v177
	s_and_saveexec_b64 s[20:21], s[40:41]
	ds_write_b32 v208, v221 offset:41088
	s_or_b64 exec, exec, s[20:21]
	v_sub_f32_e32 v113, v113, v177
	v_sub_f32_e32 v112, v112, v177
	v_sub_f32_e32 v111, v111, v177
	v_sub_f32_e32 v110, v110, v177
	v_sub_f32_e32 v109, v109, v177
	v_sub_f32_e32 v108, v108, v177
	v_sub_f32_e32 v107, v107, v177
	v_sub_f32_e32 v106, v106, v177
	v_sub_f32_e32 v105, v105, v177
	v_sub_f32_e32 v104, v104, v177
	v_sub_f32_e32 v103, v103, v177
	v_sub_f32_e32 v102, v102, v177
	v_sub_f32_e32 v101, v101, v177
	v_sub_f32_e32 v100, v100, v177
	v_sub_f32_e32 v99, v99, v177
	v_sub_f32_e32 v98, v98, v177
	v_sub_f32_e32 v230, 0x40e00000, v217
	v_mov_b32_e32 v231, v230
	v_mov_b32_e32 v232, v230
	v_mov_b32_e32 v233, v230
	v_mov_b32_e32 v234, v230
	v_mov_b32_e32 v235, v230
	v_mov_b32_e32 v236, v230
	v_mov_b32_e32 v237, v230
	v_mov_b32_e32 v238, v230
	v_mov_b32_e32 v239, v230
	v_mov_b32_e32 v240, v230
	v_mov_b32_e32 v241, v230
	v_mov_b32_e32 v242, v230
	v_mov_b32_e32 v243, v230
	v_mov_b32_e32 v244, v230
	v_mov_b32_e32 v245, v230
	v_add_u32_e32 v0, v187, v207
	s_waitcnt lgkmcnt(0)
	ds_read_b128 v[66:69], v0 offset:41184
	ds_read_b128 v[70:73], v0 offset:41152
	ds_read_b128 v[74:77], v0 offset:41120
	ds_read_b128 v[78:81], v0 offset:41088
	s_waitcnt lgkmcnt(0)
	v_pk_mul_f32 v[62:63], v[62:63], v[66:67]
	v_pk_mul_f32 v[58:59], v[58:59], v[70:71]
	v_pk_mul_f32 v[54:55], v[54:55], v[74:75]
	v_pk_mul_f32 v[64:65], v[64:65], v[68:69]
	v_pk_mul_f32 v[60:61], v[60:61], v[72:73]
	v_pk_mul_f32 v[56:57], v[56:57], v[76:77]
	v_pk_mul_f32 v[52:53], v[52:53], v[80:81]
	v_pk_mul_f32 v[50:51], v[50:51], v[78:79]
	v_pk_mul_f32 v[46:47], v[46:47], v[66:67]
	v_pk_mul_f32 v[42:43], v[42:43], v[70:71]
	v_pk_mul_f32 v[38:39], v[38:39], v[74:75]
	v_pk_mul_f32 v[48:49], v[48:49], v[68:69]
	v_pk_mul_f32 v[44:45], v[44:45], v[72:73]
	v_pk_mul_f32 v[40:41], v[40:41], v[76:77]
	v_pk_mul_f32 v[36:37], v[36:37], v[80:81]
	v_pk_mul_f32 v[34:35], v[34:35], v[78:79]
	v_pk_mul_f32 v[30:31], v[30:31], v[66:67]
	v_pk_mul_f32 v[26:27], v[26:27], v[70:71]
	v_pk_mul_f32 v[22:23], v[22:23], v[74:75]
	v_pk_mul_f32 v[32:33], v[32:33], v[68:69]
	v_pk_mul_f32 v[28:29], v[28:29], v[72:73]
	v_pk_mul_f32 v[24:25], v[24:25], v[76:77]
	v_pk_mul_f32 v[20:21], v[20:21], v[80:81]
	v_pk_mul_f32 v[18:19], v[18:19], v[78:79]
	v_pk_mul_f32 v[14:15], v[14:15], v[66:67]
	v_pk_mul_f32 v[10:11], v[10:11], v[70:71]
	v_pk_mul_f32 v[6:7], v[6:7], v[74:75]
	v_pk_mul_f32 v[16:17], v[16:17], v[68:69]
	v_pk_mul_f32 v[12:13], v[12:13], v[72:73]
	v_pk_mul_f32 v[8:9], v[8:9], v[76:77]
	v_pk_mul_f32 v[4:5], v[4:5], v[80:81]
	v_pk_mul_f32 v[2:3], v[2:3], v[78:79]
	s_branch .Lmla_h0_cont
.Lmla_h1_newmax:
	v_add_f32_e32 v0, 0xc0c00000, v177
	v_max_f32_e32 v177, 0, v0
	v_exp_f32_e64 v218, -v177
	v_add_f32_e32 v217, v217, v177
	v_sub_f32_e32 v97, v97, v177
	v_sub_f32_e32 v96, v96, v177
	v_sub_f32_e32 v95, v95, v177
	v_sub_f32_e32 v94, v94, v177
	v_sub_f32_e32 v93, v93, v177
	v_sub_f32_e32 v92, v92, v177
	v_sub_f32_e32 v91, v91, v177
	v_sub_f32_e32 v90, v90, v177
	v_sub_f32_e32 v89, v89, v177
	v_sub_f32_e32 v88, v88, v177
	v_sub_f32_e32 v87, v87, v177
	v_sub_f32_e32 v86, v86, v177
	v_sub_f32_e32 v85, v85, v177
	v_sub_f32_e32 v84, v84, v177
	v_sub_f32_e32 v83, v83, v177
	v_sub_f32_e32 v82, v82, v177
	s_and_saveexec_b64 s[20:21], s[40:41]
	ds_write_b32 v208, v218 offset:41088
	s_or_b64 exec, exec, s[20:21]
	v_sub_f32_e32 v81, v81, v177
	v_sub_f32_e32 v80, v80, v177
	v_sub_f32_e32 v79, v79, v177
	v_sub_f32_e32 v78, v78, v177
	v_sub_f32_e32 v77, v77, v177
	v_sub_f32_e32 v76, v76, v177
	v_sub_f32_e32 v75, v75, v177
	v_sub_f32_e32 v74, v74, v177
	v_sub_f32_e32 v73, v73, v177
	v_sub_f32_e32 v72, v72, v177
	v_sub_f32_e32 v71, v71, v177
	v_sub_f32_e32 v70, v70, v177
	v_sub_f32_e32 v69, v69, v177
	v_sub_f32_e32 v68, v68, v177
	v_sub_f32_e32 v67, v67, v177
	v_sub_f32_e32 v66, v66, v177
	v_sub_f32_e32 v230, 0x40e00000, v217
	v_mov_b32_e32 v231, v230
	v_mov_b32_e32 v232, v230
	v_mov_b32_e32 v233, v230
	v_mov_b32_e32 v234, v230
	v_mov_b32_e32 v235, v230
	v_mov_b32_e32 v236, v230
	v_mov_b32_e32 v237, v230
	v_mov_b32_e32 v238, v230
	v_mov_b32_e32 v239, v230
	v_mov_b32_e32 v240, v230
	v_mov_b32_e32 v241, v230
	v_mov_b32_e32 v242, v230
	v_mov_b32_e32 v243, v230
	v_mov_b32_e32 v244, v230
	v_mov_b32_e32 v245, v230
	v_add_u32_e32 v0, v187, v207
	s_waitcnt lgkmcnt(0)
	ds_read_b128 v[98:101], v0 offset:41184
	ds_read_b128 v[102:105], v0 offset:41152
	ds_read_b128 v[106:109], v0 offset:41120
	ds_read_b128 v[110:113], v0 offset:41088
	s_waitcnt lgkmcnt(0)
	v_pk_mul_f32 v[62:63], v[62:63], v[98:99]
	v_pk_mul_f32 v[58:59], v[58:59], v[102:103]
	v_pk_mul_f32 v[54:55], v[54:55], v[106:107]
	v_pk_mul_f32 v[64:65], v[64:65], v[100:101]
	v_pk_mul_f32 v[60:61], v[60:61], v[104:105]
	v_pk_mul_f32 v[56:57], v[56:57], v[108:109]
	v_pk_mul_f32 v[52:53], v[52:53], v[112:113]
	v_pk_mul_f32 v[50:51], v[50:51], v[110:111]
	v_pk_mul_f32 v[46:47], v[46:47], v[98:99]
	v_pk_mul_f32 v[42:43], v[42:43], v[102:103]
	v_pk_mul_f32 v[38:39], v[38:39], v[106:107]
	v_pk_mul_f32 v[48:49], v[48:49], v[100:101]
	v_pk_mul_f32 v[44:45], v[44:45], v[104:105]
	v_pk_mul_f32 v[40:41], v[40:41], v[108:109]
	v_pk_mul_f32 v[36:37], v[36:37], v[112:113]
	v_pk_mul_f32 v[34:35], v[34:35], v[110:111]
	v_pk_mul_f32 v[30:31], v[30:31], v[98:99]
	v_pk_mul_f32 v[26:27], v[26:27], v[102:103]
	v_pk_mul_f32 v[22:23], v[22:23], v[106:107]
	v_pk_mul_f32 v[32:33], v[32:33], v[100:101]
	v_pk_mul_f32 v[28:29], v[28:29], v[104:105]
	v_pk_mul_f32 v[24:25], v[24:25], v[108:109]
	v_pk_mul_f32 v[20:21], v[20:21], v[112:113]
	v_pk_mul_f32 v[18:19], v[18:19], v[110:111]
	v_pk_mul_f32 v[14:15], v[14:15], v[98:99]
	v_pk_mul_f32 v[10:11], v[10:11], v[102:103]
	v_pk_mul_f32 v[6:7], v[6:7], v[106:107]
	v_pk_mul_f32 v[16:17], v[16:17], v[100:101]
	v_pk_mul_f32 v[12:13], v[12:13], v[104:105]
	v_pk_mul_f32 v[8:9], v[8:9], v[108:109]
	v_pk_mul_f32 v[4:5], v[4:5], v[112:113]
	v_pk_mul_f32 v[2:3], v[2:3], v[110:111]
	s_branch .Lmla_h1_cont

; #define SWRITE(b) do { *(bf16x8*)(V_lds + (b) * SHM_V + vst0) = vs0; *(bf16x8*)(V_lds + (b) * SHM_V + vst1) = vs1; const int kc = sc * 2;  \
;     *(bf16x8*)(K_lds + (b) * SHM_K + KSWZ(sr, kc)) = ks0; *(bf16x8*)(K_lds + (b) * SHM_K + KSWZ(32 + sr, kc)) = ks1; \
;     if constexpr (NR > 0) *(bf16x8*)(Kr_lds + (b) * SHM_KR + krst) = kr; } while (0)
; #define SWRITE(b) do { *(bf16x8*)(V_lds + (b) * SHM_V + vst0) = vs0; *(bf16x8*)(V_lds + (b) * SHM_V + vst0 + 8192) = vs1;  \
;     *(bf16x8*)(K_lds + (b) * SHM_K + kst0) = ks0; *(bf16x8*)(K_lds + (b) * SHM_K + kst0 + 8192) = ks1; \
;     if constexpr (NR > 0) *(bf16x8*)(Kr_lds + (b) * SHM_KR + krst) = kr; } while (0)
; #define SWRITE(b) do { *(bf16x8*)(V_lds + (b) * 16384 + vst0) = vs0; *(bf16x8*)(V_lds + (b) * 16384 + vst0 + 8192) = vs1;  \
;     *(v4i32*)(Kn_lds + (b) * 8192 + knst) = kn; if (krw) *(v4i32*)(Kr_lds + (b) * 4096 + krst) = kr; } while (0)
; #define SWRITE(b) do { *(v4i32*)(Vt_lds + (b) * 8192 + vtst) = vt; *(v4i32*)(Kn_lds + (b) * 8192 + knst) = kn; if (krw) *(v4i32*)(Kr_lds + (b) * 4096 + krst) = kr; } while (0)
; __device__ __forceinline__ void partialSM9(f32x16& p0, f32x16& p1, float& m_run, float& alpha, const float thr2) {
;     ...
;   if (__builtin_expect(__all(pmax <= 7.0f + thr2), 1)) { alpha = 1.f; }
;   else { const float delta = fmaxf(pmax - 7.0f, 0.f); alpha = __builtin_amdgcn_exp2f(-delta); m_run += delta;
; #pragma unroll
;     for (int r = 0; r < 16; ++r) { p0[r] -= delta; p1[r] -= delta; } }
; }
; __device__ __forceinline__ void attn_unit7(const unsigned char* __restrict__ Q8, int ldq, const unsigned char* __restrict__ Kn8, int ldk, const unsigned char* __restrict__ Kr8, ...
;     ...
;   qkt9(pA0, pA1, Kn_lds, Kr_lds, qf, 7.0f - m_reg, r32, hi); partialSM9(pA0, pA1, m_reg, alA, thr_raw);
;   SWRITE(1); __syncthreads();
.LBB0_1350:
	v_add_f32_e32 v0, 0xc0c00000, v0
	v_max_f32_e32 v217, 0, v0
	v_exp_f32_e64 v218, -v217
	v_sub_f32_e32 v97, v97, v217
	v_sub_f32_e32 v96, v96, v217
	v_sub_f32_e32 v95, v95, v217
	v_sub_f32_e32 v94, v94, v217
	v_sub_f32_e32 v93, v93, v217
	v_sub_f32_e32 v92, v92, v217
	v_sub_f32_e32 v91, v91, v217
	v_sub_f32_e32 v90, v90, v217
	v_sub_f32_e32 v89, v89, v217
	v_sub_f32_e32 v88, v88, v217
	v_sub_f32_e32 v87, v87, v217
	v_sub_f32_e32 v86, v86, v217
	v_sub_f32_e32 v85, v85, v217
	v_sub_f32_e32 v84, v84, v217
	v_sub_f32_e32 v83, v83, v217
	v_sub_f32_e32 v82, v82, v217
	v_sub_f32_e32 v81, v81, v217
	v_sub_f32_e32 v80, v80, v217
	v_sub_f32_e32 v79, v79, v217
	v_sub_f32_e32 v78, v78, v217
	v_sub_f32_e32 v77, v77, v217
	v_sub_f32_e32 v76, v76, v217
	v_sub_f32_e32 v75, v75, v217
	v_sub_f32_e32 v74, v74, v217
	v_sub_f32_e32 v73, v73, v217
	v_sub_f32_e32 v72, v72, v217
	v_sub_f32_e32 v71, v71, v217
	v_sub_f32_e32 v70, v70, v217
	v_sub_f32_e32 v69, v69, v217
	v_sub_f32_e32 v68, v68, v217
	v_sub_f32_e32 v67, v67, v217
	v_sub_f32_e32 v66, v66, v217
	s_waitcnt vmcnt(0)
	ds_write_b128 v210, v[2:5] offset:8192
	ds_write_b128 v211, v[6:9] offset:24576
	s_and_saveexec_b64 s[20:21], s[42:43]
	s_cbranch_execnz .LBB0_1319
	s_branch .LBB0_1320
